# MLA attention loop software-pipelined (QK of next tile overlapped with softmax/PV), FOX loop rescheduled + V^T perm + early ncl load
# speedup vs baseline: 1.0413x; 1.0144x over previous
; DI float xhalf_other(float x, int h) { auto r = __builtin_amdgcn_permlane32_swap(__float_as_uint(x), __float_as_uint(x), false, false); return h ? __uint_as_float(r[0]) : __uint_as_float(r[1]); }
;     ...
;     float qn = 0.f;
;     if (MODE == 0 && DESC) {
; #pragma unroll
;         for (int s = 0; s < NKS; ++s)
; #pragma unroll
;             for (int j = 0; j < 8; ++j) { const float a = __uint_as_float(((unsigned)(unsigned short)qf[s][j]) << 16); qn += a * a; }
;         qn += xhalf_other(qn, h);
;         qn = sqrtf(qn) * kmax;
;     }
;     f32x16 o0, o1;
; #pragma unroll
;     for (int i = 0; i < 16; ++i) { o0[i] = 0.f; o1[i] = 0.f; }
;     float m = -INFINITY, lsum = 0.f, R = 1.f;
;     u32x4 rk[NKL], rv[2]; f32x4 rc = {0.f, 0.f, 0.f, 0.f};
;     const unsigned okk = (unsigned)(((tid / KCH) * DQK + (tid % KCH) * 8) * 2);
;     const unsigned ovv = (unsigned)(((tid >> 3) * ldv + (tid & 7) * 8) * 2), svv = (unsigned)(ldv * 64);
;     auto ld_tile = [&](int kt) {
;         const unsigned char* Kt = (const unsigned char*)(K + (size_t)(64 * kt) * DQK);
;         const unsigned char* Vt = (const unsigned char*)(VT + 64 * kt);
; #pragma unroll
;         for (int j = 0; j < NKL; ++j) rk[j] = *(const u32x4*)(Kt + (okk + j * 4096));
; #pragma unroll
;         for (int j = 0; j < 2; ++j) rv[j] = *(const u32x4*)(Vt + (ovv + j * svv));
;         if (cdec && tid < 16) rc = *(const f32x4*)(cdec + 64 * kt + 4 * tid);
;     };
;     auto st_tile = [&](int buf) {
;         bf16_t* sK = (bf16_t*)(smem + buf * ATT_BUF); bf16_t* sV = (bf16_t*)(smem + buf * ATT_BUF + 13312); float* sC = (float*)(smem + buf * ATT_BUF + 22528);
; #pragma unroll
;         for (int j = 0; j < NKL; ++j) { const int c = tid + 256 * j, row = c / KCH, kc = (c % KCH) * 8; *(u32x4*)(sK + row * KS + kc) = rk[j]; }
; #pragma unroll
;         for (int j = 0; j < 2; ++j) { const int c = tid + 256 * j, row = c >> 3, kc = (c & 7) * 8; *(u32x4*)(sV + row * LS + kc) = rv[j]; }
;         if (cdec && tid < 16) *(f32x4*)(sC + 4 * tid) = rc;
;     };
;     ld_tile(DESC ? ntiles - 1 : 0);
;     __syncthreads();
;     st_tile(0);
.LBB0_739:
	s_or_b64 exec, exec, s[6:7]
	v_ashrrev_i32_e32 v11, 31, v8
	v_lshrrev_b32_e32 v11, 29, v11
	v_add_u32_e32 v11, v8, v11
	v_lshrrev_b32_e32 v12, 3, v11
	v_and_b32_e32 v11, -8, v11
	s_movk_i32 s0, 0x48
	v_sub_u32_e32 v11, v8, v11
	v_mul_lo_u32 v12, v12, s0
	v_lshlrev_b32_e32 v113, 1, v12
	v_lshlrev_b32_e32 v12, 4, v11
	v_add3_u32 v12, s33, v113, v12
	v_add_u32_e32 v13, 0x100, v8
	s_waitcnt lgkmcnt(0)
	s_barrier
	s_waitcnt vmcnt(0)
	ds_write_b128 v12, v[82:85]
	v_ashrrev_i32_e32 v12, 31, v13
	v_lshrrev_b32_e32 v12, 29, v12
	v_add_u32_e32 v12, v13, v12
	v_lshrrev_b32_e32 v14, 3, v12
	v_and_b32_e32 v12, -8, v12
	v_sub_u32_e32 v12, v13, v12
	v_mul_lo_u32 v14, v14, s0
	v_lshlrev_b32_e32 v125, 1, v14
	v_lshlrev_b32_e32 v14, 4, v12
	v_add3_u32 v14, s33, v125, v14
	ds_write_b128 v14, v[86:89]
	v_lshrrev_b32_e32 v14, 3, v8
	v_lshlrev_b32_e32 v15, 3, v8
	v_lshrrev_b32_e32 v13, 3, v13
	v_and_b32_e32 v15, 56, v15
	v_mul_lo_u32 v14, v14, s0
	v_mul_lo_u32 v13, v13, s0
	v_lshlrev_b32_e32 v126, 1, v14
	v_lshlrev_b32_e32 v127, 1, v15
	v_and_b32_e32 v230, 1, v215
	v_lshlrev_b32_e32 v230, 3, v230
	v_sub_u32_e32 v230, v127, v230
	v_add_u32_e32 v230, 0x3400, v230
	v_lshlrev_b32_e32 v128, 1, v13
	v_add3_u32 v14, s33, v126, v230
	v_add3_u32 v13, s33, v128, v230
	ds_write2_b64 v14, v[90:91], v[92:93] offset1:2
	ds_write2_b64 v13, v[94:95], v[96:97] offset1:2
	s_and_saveexec_b64 s[6:7], vcc
	s_xor_b64 s[6:7], exec, s[6:7]
	v_mov_b32_e32 v111, v1
	s_andn2_saveexec_b64 s[6:7], s[6:7]
	v_ashrrev_i32_e32 v111, 31, v110
	v_lshl_add_u32 v13, v110, 2, s33
	ds_write_b128 v13, v[98:101] offset:22528
	s_or_b64 exec, exec, s[6:7]
	s_mov_b32 s0, 0xf800000
	v_mul_f32_e32 v13, 0x4f800000, v6
	v_cmp_gt_f32_e32 vcc, s0, v6
	v_lshlrev_b32_e32 v18, 3, v11
	v_lshlrev_b32_e32 v19, 3, v12
	v_cndmask_b32_e32 v6, v6, v13, vcc
	v_sqrt_f32_e32 v13, v6
	v_and_b32_e32 v8, 63, v8
	v_add_u32_e32 v130, s94, v5
	v_cmp_class_f32_e64 s[8:9], v6, v220
	v_add_u32_e32 v11, -1, v13
	v_fma_f32 v12, -v11, v13, v6
	v_cmp_ge_f32_e64 s[6:7], 0, v12
	v_add_u32_e32 v12, 1, v13
	v_mul_u32_u24_e32 v20, 0x48, v3
	v_cndmask_b32_e64 v11, v13, v11, s[6:7]
	v_fma_f32 v13, -v12, v13, v6
	v_cmp_lt_f32_e64 s[6:7], 0, v13
	v_mov_b32_e32 v16, v1
	v_mov_b32_e32 v17, v1
	v_cndmask_b32_e64 v11, v11, v12, s[6:7]
	v_cmp_gt_u32_e64 s[6:7], 32, v8
	v_mul_f32_e32 v12, 0x37800000, v11
	v_cndmask_b32_e32 v11, v11, v12, vcc
	v_cndmask_b32_e64 v9, v9, v10, s[6:7]
	v_add_f32_e32 v7, v7, v9
	v_mul_f32_e32 v9, 0x4f800000, v7
	v_cmp_gt_f32_e32 vcc, s0, v7
	v_cndmask_b32_e64 v6, v11, v6, s[8:9]
	v_mul_f32_e32 v6, 0x3f80068e, v6
	v_cndmask_b32_e32 v7, v7, v9, vcc
	v_sqrt_f32_e32 v9, v7
	v_readlane_b32 s0, v255, 6
	v_lshlrev_b32_e32 v129, 3, v4
	v_or_b32_e32 v131, v130, v3
	v_add_u32_e32 v5, -1, v9
	v_fma_f32 v10, -v5, v9, v7
	v_cmp_ge_f32_e64 s[8:9], 0, v10
	v_add_u32_e32 v10, 1, v9
	v_lshlrev_b32_e32 v112, 2, v4
	v_cndmask_b32_e64 v5, v9, v5, s[8:9]
	v_fma_f32 v9, -v10, v9, v7
	v_cmp_lt_f32_e64 s[8:9], 0, v9
	v_lshl_add_u32 v134, v2, 2, s0
	v_mov_b32_e32 v2, v1
	v_cndmask_b32_e64 v5, v5, v10, s[8:9]
	v_mul_f32_e32 v9, 0x37800000, v5
	v_cndmask_b32_e32 v5, v5, v9, vcc
	v_cmp_class_f32_e32 vcc, v7, v220
	v_cmp_eq_u32_e64 s[8:9], 0, v8
	v_mov_b32_e32 v3, v1
	v_cndmask_b32_e32 v5, v5, v7, vcc
	v_mul_f32_e32 v132, v6, v5
	v_mov_b32_e32 v4, v1
	v_mov_b32_e32 v5, v1
	v_mov_b32_e32 v6, v1
	v_mov_b32_e32 v7, v1
	v_mov_b32_e32 v8, v1
	v_mov_b32_e32 v9, v1
	v_mov_b32_e32 v10, v1
	v_mov_b32_e32 v11, v1
	v_mov_b32_e32 v12, v1
	v_mov_b32_e32 v13, v1
	v_mov_b32_e32 v14, v1
	v_mov_b32_e32 v15, v1
	v_lshlrev_b32_e32 v136, 1, v20
	v_lshlrev_b32_e32 v137, 1, v18
	v_lshlrev_b32_e32 v138, 1, v19
	v_mov_b64_e32 v[32:33], v[16:17]
	s_mov_b32 s28, 0
	v_lshl_add_u64 v[114:115], v[110:111], 2, s[12:13]
	v_or_b32_e32 v133, 31, v130
	v_sub_u32_e32 v135, 0, v129
	v_mov_b32_e32 v139, 0xff800000
	v_mov_b32_e32 v111, 0
	s_mov_b32 s14, s94
	v_mov_b64_e32 v[30:31], v[14:15]
	v_mov_b64_e32 v[28:29], v[12:13]
	v_mov_b64_e32 v[26:27], v[10:11]
	v_mov_b64_e32 v[24:25], v[8:9]
	v_mov_b64_e32 v[22:23], v[6:7]
	v_mov_b64_e32 v[20:21], v[4:5]
	v_mov_b64_e32 v[18:19], v[2:3]
	s_mov_b32 s20, 0
	s_cmp_eq_u32 s27, -1
	s_cbranch_scc1 .LBB0_759

; #define MFMA32(a, b, c) __builtin_amdgcn_mfma_f32_32x32x16_bf16((a), (b), (c), 0, 0, 0)
;     ...
;         const bf16_t* sK = (const bf16_t*)(smem + buf * ATT_BUF); const bf16_t* sV = (const bf16_t*)(smem + buf * ATT_BUF + 13312);
;         const float* sC = (const float*)(smem + buf * ATT_BUF + 22528);
;         bool active = true;
;         if (MODE == 0) active = (64 * kt <= q0 + 32 * w + 31);
;         if (MODE == 1) active = (64 * kt < q0 + 32 * w + 31);
;         if (active) {
;             f32x16 sc[2];
; #pragma unroll
;             for (int i = 0; i < 16; ++i) { sc[0][i] = 0.f; sc[1][i] = 0.f; }
; #pragma unroll
;             for (int s = 0; s < NKS; ++s) {
;                 const bf16x8 k0 = *(const bf16x8*)(sK + r * KS + 16 * s + 8 * h), k1 = *(const bf16x8*)(sK + (32 + r) * KS + 16 * s + 8 * h);
;                 sc[0] = MFMA32(k0, qf[s], sc[0]);
;                 sc[1] = MFMA32(k1, qf[s], sc[1]);
;             }
;     ...
;                 if (cdec) {
; #pragma unroll
;                     for (int mt = 0; mt < 2; ++mt)
; #pragma unroll
;                         for (int qd = 0; qd < 4; ++qd) s4[mt][qd] += *(const f32x4*)(sC + 32 * mt + 8 * qd + 4 * h);
;                 }
;                 if (MODE == 0 && (64 * kt + 63 > q0 + 32 * w)) {
; #pragma unroll
;                     for (int mt = 0; mt < 2; ++mt)
; #pragma unroll
;                         for (int qd = 0; qd < 4; ++qd)
; #pragma unroll
;                             for (int e = 0; e < 4; ++e)
;                                 if (64 * kt + 32 * mt + 8 * qd + 4 * h + e > qidx) s4[mt][qd][e] = -INFINITY;
;                 }
.LBB0_750:
	s_andn2_b64 vcc, exec, s[18:19]
	s_mov_b64 s[18:19], 0
	s_cbranch_vccnz .LBB0_768
	s_add_i32 s48, s14, 64
	s_and_b32 s15, s20, 1
	v_cmp_le_i32_e32 vcc, s48, v133
	s_and_saveexec_b64 s[18:19], vcc
	s_cbranch_execz .LBB0_757
	s_mul_i32 s20, s15, 0x5900
	s_add_i32 s20, s33, s20
	v_lshlrev_b32_e32 v34, 1, v129
	v_add3_u32 v212, s20, v136, v34
	v_lshl_add_u32 v213, v112, 2, s20
	ds_read_b128 v[176:179], v212
	ds_read_b128 v[180:183], v212 offset:4608
	s_add_i32 s20, s14, 0x7f
	ds_read_b128 v[184:187], v212 offset:32
	ds_read_b128 v[188:191], v212 offset:4640
	v_cmp_gt_i32_e32 vcc, s20, v130
	ds_read_b128 v[192:195], v212 offset:64
	ds_read_b128 v[196:199], v212 offset:4672
	ds_read_b128 v[200:203], v212 offset:96
	ds_read_b128 v[204:207], v212 offset:4704
	ds_read_b128 v[208:211], v213 offset:22528
	ds_read_b128 v[232:235], v213 offset:22560
	ds_read_b128 v[236:239], v213 offset:22592
	ds_read_b128 v[240:243], v213 offset:22624
	ds_read_b128 v[244:247], v213 offset:22656
	ds_read_b128 v[248:251], v213 offset:22688
	ds_read_b128 v[116:119], v213 offset:22720
	s_waitcnt lgkmcnt(13)
	v_mfma_f32_32x32x16_bf16 v[50:65], v[176:179], v[66:69], 0
	v_mfma_f32_32x32x16_bf16 v[34:49], v[180:183], v[66:69], 0
	ds_read_b128 v[120:123], v213 offset:22752
	s_waitcnt lgkmcnt(12)
	v_mfma_f32_32x32x16_bf16 v[50:65], v[184:187], v[70:73], v[50:65]
	v_mfma_f32_32x32x16_bf16 v[34:49], v[188:191], v[70:73], v[34:49]
	s_waitcnt lgkmcnt(10)
	v_mfma_f32_32x32x16_bf16 v[50:65], v[192:195], v[74:77], v[50:65]
	v_mfma_f32_32x32x16_bf16 v[34:49], v[196:199], v[74:77], v[34:49]
	s_waitcnt lgkmcnt(8)
	v_mfma_f32_32x32x16_bf16 v[50:65], v[200:203], v[78:81], v[50:65]
	v_mfma_f32_32x32x16_bf16 v[34:49], v[204:207], v[78:81], v[34:49]
	s_waitcnt lgkmcnt(0)
	ds_read_b128 v[176:179], v212 offset:13312
	ds_read_b128 v[180:183], v212 offset:17920
	ds_read_b128 v[184:187], v212 offset:13344
	ds_read_b128 v[188:191], v212 offset:17952
	ds_read_b128 v[192:195], v212 offset:13376
	ds_read_b128 v[196:199], v212 offset:17984
	ds_read_b128 v[200:203], v212 offset:13408
	ds_read_b128 v[204:207], v212 offset:18016
	s_nop 2
	v_pk_add_f32 v[50:51], v[50:51], v[208:209]
	v_pk_add_f32 v[52:53], v[52:53], v[210:211]
	v_pk_add_f32 v[54:55], v[54:55], v[232:233]
	v_pk_add_f32 v[56:57], v[56:57], v[234:235]
	v_pk_add_f32 v[58:59], v[58:59], v[236:237]
	v_pk_add_f32 v[60:61], v[60:61], v[238:239]
	v_pk_add_f32 v[62:63], v[62:63], v[240:241]
	v_pk_add_f32 v[64:65], v[64:65], v[242:243]
	v_pk_add_f32 v[34:35], v[34:35], v[244:245]
	v_pk_add_f32 v[36:37], v[36:37], v[246:247]
	v_pk_add_f32 v[38:39], v[38:39], v[248:249]
	v_pk_add_f32 v[40:41], v[40:41], v[250:251]
	v_pk_add_f32 v[42:43], v[42:43], v[116:117]
	v_pk_add_f32 v[44:45], v[44:45], v[118:119]
	v_pk_add_f32 v[46:47], v[46:47], v[120:121]
	v_pk_add_f32 v[48:49], v[48:49], v[122:123]
	s_and_saveexec_b64 s[20:21], vcc
	s_cbranch_execz .Lfox_nomask
	v_sub_u32_e32 v217, v131, v112
	v_subrev_u32_e32 v217, s48, v217
	v_cmp_le_i32_e32 vcc, 0, v217
	s_nop 1
	v_cndmask_b32_e32 v50, v228, v50, vcc
	v_cmp_le_i32_e32 vcc, 1, v217
	s_nop 1
	v_cndmask_b32_e32 v51, v228, v51, vcc
	v_cmp_le_i32_e32 vcc, 2, v217
	s_nop 1
	v_cndmask_b32_e32 v52, v228, v52, vcc
	v_cmp_le_i32_e32 vcc, 3, v217
	s_nop 1
	v_cndmask_b32_e32 v53, v228, v53, vcc
	v_cmp_le_i32_e32 vcc, 8, v217
	s_nop 1
	v_cndmask_b32_e32 v54, v228, v54, vcc
	v_cmp_le_i32_e32 vcc, 9, v217
	s_nop 1
	v_cndmask_b32_e32 v55, v228, v55, vcc
	v_cmp_le_i32_e32 vcc, 10, v217
	s_nop 1
	v_cndmask_b32_e32 v56, v228, v56, vcc
	v_cmp_le_i32_e32 vcc, 11, v217
	s_nop 1
	v_cndmask_b32_e32 v57, v228, v57, vcc
	v_cmp_le_i32_e32 vcc, 16, v217
	s_nop 1
	v_cndmask_b32_e32 v58, v228, v58, vcc
	v_cmp_le_i32_e32 vcc, 17, v217
	s_nop 1
	v_cndmask_b32_e32 v59, v228, v59, vcc
	v_cmp_le_i32_e32 vcc, 18, v217
	s_nop 1
	v_cndmask_b32_e32 v60, v228, v60, vcc
	v_cmp_le_i32_e32 vcc, 19, v217
	s_nop 1
	v_cndmask_b32_e32 v61, v228, v61, vcc
	v_cmp_le_i32_e32 vcc, 24, v217
	s_nop 1
	v_cndmask_b32_e32 v62, v228, v62, vcc
	v_cmp_le_i32_e32 vcc, 25, v217
	s_nop 1
	v_cndmask_b32_e32 v63, v228, v63, vcc
	v_cmp_le_i32_e32 vcc, 26, v217
	s_nop 1
	v_cndmask_b32_e32 v64, v228, v64, vcc
	v_cmp_le_i32_e32 vcc, 27, v217
	s_nop 1
	v_cndmask_b32_e32 v65, v228, v65, vcc
	v_cmp_le_i32_e32 vcc, 32, v217
	s_nop 1
	v_cndmask_b32_e32 v34, v228, v34, vcc
	v_cmp_le_i32_e32 vcc, 33, v217
	s_nop 1
	v_cndmask_b32_e32 v35, v228, v35, vcc
	v_cmp_le_i32_e32 vcc, 34, v217
	s_nop 1
	v_cndmask_b32_e32 v36, v228, v36, vcc
	v_cmp_le_i32_e32 vcc, 35, v217
	s_nop 1
	v_cndmask_b32_e32 v37, v228, v37, vcc
	v_cmp_le_i32_e32 vcc, 40, v217
	s_nop 1
	v_cndmask_b32_e32 v38, v228, v38, vcc
	v_cmp_le_i32_e32 vcc, 41, v217
	s_nop 1
	v_cndmask_b32_e32 v39, v228, v39, vcc
	v_cmp_le_i32_e32 vcc, 42, v217
	s_nop 1
	v_cndmask_b32_e32 v40, v228, v40, vcc
	v_cmp_le_i32_e32 vcc, 43, v217
	s_nop 1
	v_cndmask_b32_e32 v41, v228, v41, vcc
	v_cmp_le_i32_e32 vcc, 48, v217
	s_nop 1
	v_cndmask_b32_e32 v42, v228, v42, vcc
	v_cmp_le_i32_e32 vcc, 49, v217
	s_nop 1
	v_cndmask_b32_e32 v43, v228, v43, vcc
	v_cmp_le_i32_e32 vcc, 50, v217
	s_nop 1
	v_cndmask_b32_e32 v44, v228, v44, vcc
	v_cmp_le_i32_e32 vcc, 51, v217
	s_nop 1
	v_cndmask_b32_e32 v45, v228, v45, vcc
	v_cmp_le_i32_e32 vcc, 56, v217
	s_nop 1
	v_cndmask_b32_e32 v46, v228, v46, vcc
	v_cmp_le_i32_e32 vcc, 57, v217
	s_nop 1
	v_cndmask_b32_e32 v47, v228, v47, vcc
	v_cmp_le_i32_e32 vcc, 58, v217
	s_nop 1
	v_cndmask_b32_e32 v48, v228, v48, vcc
	v_cmp_le_i32_e32 vcc, 59, v217
	s_nop 1
	v_cndmask_b32_e32 v49, v228, v49, vcc
; DI unsigned pk2(float a, float b) { f32x2 v = {a, b}; return __builtin_bit_cast(unsigned, __builtin_convertvector(v, bf2_t)); }
; #define MFMA32(a, b, c) __builtin_amdgcn_mfma_f32_32x32x16_bf16((a), (b), (c), 0, 0, 0)
;     ...
;                 float mx = fmaxf(s4[0][0].x, s4[1][0].x);
; #pragma unroll
;                 for (int qd = 0; qd < 4; ++qd) {
;                     mx = fmaxf(fmaxf(mx, s4[0][qd].y), s4[1][qd].y);
;                     mx = fmaxf(fmaxf(mx, s4[0][qd].z), s4[1][qd].z);
;                     mx = fmaxf(fmaxf(mx, s4[0][qd].w), s4[1][qd].w);
;                     if (qd < 3) mx = fmaxf(fmaxf(mx, s4[0][qd + 1].x), s4[1][qd + 1].x);
;                 }
;                 mx = xhalf_max(mx);
;                 const float mn = fmaxf(m, mx), alpha = fexp2(m - mn);
;                 m = mn;
;                 f32x4 ps4 = {0.f, 0.f, 0.f, 0.f};
;                 const float nmn = -mn;
;                 const f32x4 nm4 = {nmn, nmn, nmn, nmn};
;                 if (__builtin_amdgcn_ballot_w64(alpha != 1.f) != 0) { o0 *= alpha; o1 *= alpha; }
; #pragma unroll
;                 for (int s2 = 0; s2 < 4; ++s2) {
;                     const int mt = s2 >> 1, s = s2 & 1;
;                     f32x4 da = s4[mt][2 * s] + nm4, db = s4[mt][2 * s + 1] + nm4;
;                     da.x = fexp2(da.x); da.y = fexp2(da.y); da.z = fexp2(da.z); da.w = fexp2(da.w);
;                     db.x = fexp2(db.x); db.y = fexp2(db.y); db.z = fexp2(db.z); db.w = fexp2(db.w);
;                     ps4 += da; ps4 += db;
;                     u32x4 pp;
;                     pp.x = pk2(da.x, da.y); pp.y = pk2(da.z, da.w); pp.z = pk2(db.x, db.y); pp.w = pk2(db.z, db.w);
;                     const bf16x8 pfr = __builtin_bit_cast(bf16x8, pp);
;                     const s16x4 a0 = *(const s16x4*)(sV + r * LS + 16 * s2 + 4 * h), a1 = *(const s16x4*)(sV + r * LS + 16 * s2 + 8 + 4 * h);
;                     const s16x4 b0 = *(const s16x4*)(sV + (32 + r) * LS + 16 * s2 + 4 * h), b1 = *(const s16x4*)(sV + (32 + r) * LS + 16 * s2 + 8 + 4 * h);
;                     const bf16x8 v0 = __builtin_shufflevector(a0, a1, 0, 1, 2, 3, 4, 5, 6, 7), v1 = __builtin_shufflevector(b0, b1, 0, 1, 2, 3, 4, 5, 6, 7);
;                     o0 = MFMA32(v0, pfr, o0);
;                     o1 = MFMA32(v1, pfr, o1);
;                 }
;                 lsum = lsum * alpha + ((ps4.x + ps4.y) + (ps4.z + ps4.w));
.Lfox_nomask:
	s_or_b64 exec, exec, s[20:21]
	v_max3_f32 v212, v50, v51, v52
	v_max3_f32 v213, v53, v54, v55
	v_max3_f32 v217, v56, v57, v58
	v_max3_f32 v236, v59, v60, v61
	v_max3_f32 v212, v212, v62, v63
	v_max3_f32 v213, v213, v64, v65
	v_max3_f32 v217, v217, v34, v35
	v_max3_f32 v236, v236, v36, v37
	v_max3_f32 v212, v212, v38, v39
	v_max3_f32 v213, v213, v40, v41
	v_max3_f32 v217, v217, v42, v43
	v_max3_f32 v236, v236, v44, v45
	v_max3_f32 v212, v212, v46, v47
	v_max3_f32 v213, v213, v48, v49
	v_max3_f32 v212, v212, v213, v217
	v_max_f32_e32 v212, v212, v236
	v_mov_b32_e32 v213, v212
	s_nop 1
	v_permlane32_swap_b32_e32 v212, v213
	v_max3_f32 v212, v139, v212, v213
	v_sub_f32_e32 v216, v139, v212
	v_exp_f32_e32 v216, v216
	v_mov_b32_e32 v139, v212
	v_cmp_neq_f32_e32 vcc, 1.0, v216
	s_cbranch_vccz .Lfox_norescale
	v_pk_mul_f32 v[32:33], v[32:33], v[216:217] op_sel_hi:[1,0]
	v_pk_mul_f32 v[30:31], v[30:31], v[216:217] op_sel_hi:[1,0]
	v_pk_mul_f32 v[28:29], v[28:29], v[216:217] op_sel_hi:[1,0]
	v_pk_mul_f32 v[26:27], v[26:27], v[216:217] op_sel_hi:[1,0]
	v_pk_mul_f32 v[24:25], v[24:25], v[216:217] op_sel_hi:[1,0]
	v_pk_mul_f32 v[22:23], v[22:23], v[216:217] op_sel_hi:[1,0]
	v_pk_mul_f32 v[20:21], v[20:21], v[216:217] op_sel_hi:[1,0]
	v_pk_mul_f32 v[18:19], v[18:19], v[216:217] op_sel_hi:[1,0]
	v_pk_mul_f32 v[16:17], v[16:17], v[216:217] op_sel_hi:[1,0]
	v_pk_mul_f32 v[14:15], v[14:15], v[216:217] op_sel_hi:[1,0]
	v_pk_mul_f32 v[12:13], v[12:13], v[216:217] op_sel_hi:[1,0]
	v_pk_mul_f32 v[10:11], v[10:11], v[216:217] op_sel_hi:[1,0]
	v_pk_mul_f32 v[8:9], v[8:9], v[216:217] op_sel_hi:[1,0]
	v_pk_mul_f32 v[6:7], v[6:7], v[216:217] op_sel_hi:[1,0]
	v_pk_mul_f32 v[4:5], v[4:5], v[216:217] op_sel_hi:[1,0]
	v_pk_mul_f32 v[2:3], v[2:3], v[216:217] op_sel_hi:[1,0]
.Lfox_norescale:
	v_sub_f32_e32 v50, v50, v212
	v_sub_f32_e32 v51, v51, v212
	v_sub_f32_e32 v52, v52, v212
	v_sub_f32_e32 v53, v53, v212
	v_sub_f32_e32 v54, v54, v212
	v_sub_f32_e32 v55, v55, v212
	v_sub_f32_e32 v56, v56, v212
	v_sub_f32_e32 v57, v57, v212
	v_exp_f32_e32 v50, v50
	v_exp_f32_e32 v51, v51
	v_exp_f32_e32 v52, v52
	v_exp_f32_e32 v53, v53
	v_exp_f32_e32 v54, v54
	v_exp_f32_e32 v55, v55
	v_exp_f32_e32 v56, v56
	v_exp_f32_e32 v57, v57
	v_cvt_pk_bf16_f32 v140, v50, v51
	v_cvt_pk_bf16_f32 v141, v52, v53
	v_cvt_pk_bf16_f32 v142, v54, v55
	v_cvt_pk_bf16_f32 v143, v56, v57
	s_waitcnt lgkmcnt(0)
	v_sub_f32_e32 v58, v58, v212
	v_sub_f32_e32 v59, v59, v212
	v_sub_f32_e32 v60, v60, v212
	v_sub_f32_e32 v61, v61, v212
	v_sub_f32_e32 v62, v62, v212
	v_sub_f32_e32 v63, v63, v212
	v_sub_f32_e32 v64, v64, v212
	v_sub_f32_e32 v65, v65, v212
	v_mfma_f32_32x32x16_bf16 v[18:33], v[176:179], v[140:143], v[18:33]
	v_exp_f32_e32 v58, v58
	v_exp_f32_e32 v59, v59
	v_exp_f32_e32 v60, v60
	v_exp_f32_e32 v61, v61
	v_mfma_f32_32x32x16_bf16 v[2:17], v[180:183], v[140:143], v[2:17]
	v_exp_f32_e32 v62, v62
	v_exp_f32_e32 v63, v63
	v_exp_f32_e32 v64, v64
	v_exp_f32_e32 v65, v65
	v_add_f32_e32 v236, v50, v51
	v_add_f32_e32 v237, v52, v53
	v_add_f32_e32 v238, v54, v55
	v_add_f32_e32 v239, v56, v57
	v_add_f32_e32 v236, v236, v237
	v_add_f32_e32 v238, v238, v239
	v_add_f32_e32 v240, v236, v238
	v_cvt_pk_bf16_f32 v144, v58, v59
	v_cvt_pk_bf16_f32 v145, v60, v61
	v_cvt_pk_bf16_f32 v146, v62, v63
	v_cvt_pk_bf16_f32 v147, v64, v65
	v_sub_f32_e32 v34, v34, v212
	v_sub_f32_e32 v35, v35, v212
	v_sub_f32_e32 v36, v36, v212
	v_sub_f32_e32 v37, v37, v212
	v_sub_f32_e32 v38, v38, v212
	v_sub_f32_e32 v39, v39, v212
	v_sub_f32_e32 v40, v40, v212
	v_sub_f32_e32 v41, v41, v212
	v_mfma_f32_32x32x16_bf16 v[18:33], v[184:187], v[144:147], v[18:33]
	v_exp_f32_e32 v34, v34
	v_exp_f32_e32 v35, v35
	v_exp_f32_e32 v36, v36
	v_exp_f32_e32 v37, v37
	v_mfma_f32_32x32x16_bf16 v[2:17], v[188:191], v[144:147], v[2:17]
	v_exp_f32_e32 v38, v38
	v_exp_f32_e32 v39, v39
	v_exp_f32_e32 v40, v40
	v_exp_f32_e32 v41, v41
	v_add_f32_e32 v236, v58, v59
	v_add_f32_e32 v237, v60, v61
	v_add_f32_e32 v238, v62, v63
	v_add_f32_e32 v239, v64, v65
	v_add_f32_e32 v236, v236, v237
	v_add_f32_e32 v238, v238, v239
	v_add_f32_e32 v236, v236, v238
	v_add_f32_e32 v240, v240, v236
	v_cvt_pk_bf16_f32 v208, v34, v35
	v_cvt_pk_bf16_f32 v209, v36, v37
	v_cvt_pk_bf16_f32 v210, v38, v39
	v_cvt_pk_bf16_f32 v211, v40, v41
	v_sub_f32_e32 v42, v42, v212
	v_sub_f32_e32 v43, v43, v212
	v_sub_f32_e32 v44, v44, v212
	v_sub_f32_e32 v45, v45, v212
	v_sub_f32_e32 v46, v46, v212
	v_sub_f32_e32 v47, v47, v212
	v_sub_f32_e32 v48, v48, v212
	v_sub_f32_e32 v49, v49, v212
	v_mfma_f32_32x32x16_bf16 v[18:33], v[192:195], v[208:211], v[18:33]
	v_exp_f32_e32 v42, v42
	v_exp_f32_e32 v43, v43
	v_exp_f32_e32 v44, v44
	v_exp_f32_e32 v45, v45
	v_mfma_f32_32x32x16_bf16 v[2:17], v[196:199], v[208:211], v[2:17]
	v_exp_f32_e32 v46, v46
	v_exp_f32_e32 v47, v47
	v_exp_f32_e32 v48, v48
	v_exp_f32_e32 v49, v49
	v_add_f32_e32 v236, v34, v35
	v_add_f32_e32 v237, v36, v37
	v_add_f32_e32 v238, v38, v39
	v_add_f32_e32 v239, v40, v41
	v_add_f32_e32 v236, v236, v237
	v_add_f32_e32 v238, v238, v239
	v_add_f32_e32 v236, v236, v238
	v_add_f32_e32 v240, v240, v236
	v_cvt_pk_bf16_f32 v232, v42, v43
	v_cvt_pk_bf16_f32 v233, v44, v45
	v_cvt_pk_bf16_f32 v234, v46, v47
	v_cvt_pk_bf16_f32 v235, v48, v49
	v_add_f32_e32 v236, v42, v43
	v_add_f32_e32 v237, v44, v45
	v_add_f32_e32 v238, v46, v47
	v_add_f32_e32 v239, v48, v49
	v_mfma_f32_32x32x16_bf16 v[18:33], v[200:203], v[232:235], v[18:33]
	v_mfma_f32_32x32x16_bf16 v[2:17], v[204:207], v[232:235], v[2:17]
	v_add_f32_e32 v236, v236, v237
	v_add_f32_e32 v238, v238, v239
	v_add_f32_e32 v236, v236, v238
	v_add_f32_e32 v240, v240, v236
	v_fma_f32 v111, v111, v216, v240

;     ...
;         if (MODE == 0 && DESC) {
;             const float ncl = (kt > 0) ? cdec[64 * kt - 1] : 0.f;
;             const bool live = !(qn + ncl - m < -152.f);
;             const int done = (__builtin_amdgcn_ballot_w64(live) == 0) ? 1 : 0;
;             if (lane == 0) ((int*)(smem0 + SMEM_FLAG))[(it & 1) * 8 + hf * 4 + w] = done;
;         }
;         if (it + 1 < ntiles) st_tile(buf ^ 1);
.LBB0_761:
	s_waitcnt vmcnt(0) lgkmcnt(0)
	v_add_f32_e32 v34, v132, v231
	v_sub_f32_e32 v34, v34, v139
	s_mov_b32 s18, 0xc3180000
	v_cmp_ngt_f32_e32 vcc, s18, v34
	s_and_saveexec_b64 s[18:19], s[8:9]
	s_cmp_eq_u64 vcc, 0
	s_cselect_b64 s[20:21], -1, 0
	v_cndmask_b32_e64 v34, 0, 1, s[20:21]
	v_lshl_add_u32 v35, s15, 5, v134
	ds_write_b32 v35, v34
	s_or_b64 exec, exec, s[18:19]
	s_andn2_b64 vcc, exec, s[16:17]
	s_cbranch_vccnz .LBB0_767
	s_xor_b32 s15, s15, 1
	s_mulk_i32 s15, 0x5900
	s_add_i32 s15, s33, s15
	v_add3_u32 v34, s15, v113, v137
	ds_write_b128 v34, v[82:85]
	v_add3_u32 v34, s15, v125, v138
	ds_write_b128 v34, v[86:89]
	v_add3_u32 v34, s15, v126, v230
	ds_write2_b64 v34, v[90:91], v[92:93] offset1:2
	v_add3_u32 v34, s15, v128, v230
	ds_write2_b64 v34, v[94:95], v[96:97] offset1:2
	s_and_saveexec_b64 s[16:17], s[4:5]
	v_lshl_add_u32 v34, v110, 2, s15
	ds_write_b128 v34, v[98:101] offset:22528
	s_or_b64 exec, exec, s[16:17]

;     constexpr int KS = DQK + 8, NKS = DQK / 16, KCH = DQK / 8, NKL = 64 * KCH / 256;
;     const int tid = tid_op(), lane = tid & 63, w = tid >> 6, r = lane & 31, h = lane >> 5;
;     const int qidx = q0 + 32 * w + r;
;     bf16x8 qf[NKS];
; #pragma unroll
;     for (int s = 0; s < NKS; ++s) qf[s] = *(const bf16x8*)(Q + (size_t)(32 * w + r) * DQK + 16 * s + 8 * h);
;     float qn = 0.f;
;     if (MODE == 0 && DESC) {
; #pragma unroll
;         for (int s = 0; s < NKS; ++s)
; #pragma unroll
;             for (int j = 0; j < 8; ++j) { const float a = __uint_as_float(((unsigned)(unsigned short)qf[s][j]) << 16); qn += a * a; }
;         qn += xhalf_other(qn, h);
;         qn = sqrtf(qn) * kmax;
;     }
;     f32x16 o0, o1;
; #pragma unroll
;     for (int i = 0; i < 16; ++i) { o0[i] = 0.f; o1[i] = 0.f; }
;     float m = -INFINITY, lsum = 0.f, R = 1.f;
;     u32x4 rk[NKL], rv[2]; f32x4 rc = {0.f, 0.f, 0.f, 0.f};
;     const unsigned okk = (unsigned)(((tid / KCH) * DQK + (tid % KCH) * 8) * 2);
;     const unsigned ovv = (unsigned)(((tid >> 3) * ldv + (tid & 7) * 8) * 2), svv = (unsigned)(ldv * 64);
;     auto ld_tile = [&](int kt) {
;         const unsigned char* Kt = (const unsigned char*)(K + (size_t)(64 * kt) * DQK);
;         const unsigned char* Vt = (const unsigned char*)(VT + 64 * kt);
; #pragma unroll
;         for (int j = 0; j < NKL; ++j) rk[j] = *(const u32x4*)(Kt + (okk + j * 4096));
; #pragma unroll
;         for (int j = 0; j < 2; ++j) rv[j] = *(const u32x4*)(Vt + (ovv + j * svv));
;         if (cdec && tid < 16) rc = *(const f32x4*)(cdec + 64 * kt + 4 * tid);
;     };
;     auto st_tile = [&](int buf) {
;         bf16_t* sK = (bf16_t*)(smem + buf * ATT_BUF); bf16_t* sV = (bf16_t*)(smem + buf * ATT_BUF + 13312); float* sC = (float*)(smem + buf * ATT_BUF + 22528);
; #pragma unroll
;         for (int j = 0; j < NKL; ++j) { const int c = tid + 256 * j, row = c / KCH, kc = (c % KCH) * 8; *(u32x4*)(sK + row * KS + kc) = rk[j]; }
; #pragma unroll
;         for (int j = 0; j < 2; ++j) { const int c = tid + 256 * j, row = c >> 3, kc = (c & 7) * 8; *(u32x4*)(sV + row * LS + kc) = rv[j]; }
;         if (cdec && tid < 16) *(f32x4*)(sC + 4 * tid) = rc;
;     };
;     ld_tile(DESC ? ntiles - 1 : 0);
;     __syncthreads();
;     st_tile(0);
; #pragma unroll 1
;     for (int it = 0; it < ntiles; ++it) {
.LBB0_771:
	s_and_b64 vcc, exec, s[4:5]
	s_cbranch_vccz .LBB0_786
	s_lshl_b64 s[4:5], s[10:11], 13
	s_or_b32 s4, s4, s94
	s_mulk_i32 s5, 0xc0
	s_mul_hi_u32 s6, s4, 0xc0
	s_add_i32 s5, s6, s5
	s_mulk_i32 s4, 0xc0
	v_readlane_b32 s0, v254, 58
	s_add_u32 s6, s0, s4
	v_readlane_b32 s0, v254, 59
	v_mov_b32_e32 v8, v215
	s_addc_u32 s7, s0, s5
	s_mul_i32 s4, s10, 0x180000
	v_ashrrev_i32_e32 v9, 1, v8
	v_readlane_b32 s0, v254, 60
	v_bfe_u32 v121, v8, 5, 1
	v_bfi_b32 v110, s41, v9, v8
	v_mov_b64_e32 v[2:3], s[6:7]
	s_mul_hi_u32 s5, s10, 0x180000
	s_add_u32 s4, s0, s4
	v_readlane_b32 s0, v254, 61
	v_mad_i64_i32 v[2:3], s[6:7], v110, s85, v[2:3]
	v_lshlrev_b32_e32 v0, 4, v121
	s_addc_u32 s5, s0, s5
	v_lshl_add_u64 v[2:3], v[2:3], 0, v[0:1]
	v_lshlrev_b32_e32 v0, 4, v8
	v_lshl_add_u64 v[4:5], s[4:5], 0, v[0:1]
	v_add_u32_e32 v112, 0x1000, v0
	v_mov_b32_e32 v113, v1
	v_lshl_add_u64 v[6:7], s[4:5], 0, v[112:113]
	flat_load_dwordx4 v[66:69], v[4:5]
	flat_load_dwordx4 v[70:73], v[6:7]
	v_add_u32_e32 v114, 0x2000, v0
	v_mov_b32_e32 v115, v1
	s_lshl_b64 s[6:7], s[10:11], 20
	v_lshl_add_u64 v[4:5], s[4:5], 0, v[114:115]
	v_readlane_b32 s0, v254, 62
	flat_load_dwordx4 v[74:77], v[4:5]
	s_add_u32 s6, s0, s6
	v_readlane_b32 s0, v254, 63
	s_addc_u32 s7, s0, s7
	v_lshlrev_b32_e32 v4, 11, v8
	v_and_b32_e32 v5, 0x70, v0
	s_movk_i32 s0, 0xc000
	v_and_or_b32 v116, v4, s0, v5
	v_mov_b32_e32 v117, v1
	v_lshl_add_u64 v[4:5], s[6:7], 0, v[116:117]
	flat_load_dwordx4 v[78:81], v[4:5]
	v_add_u32_e32 v118, 0x80000, v116
	v_mov_b32_e32 v119, v1
	v_lshl_add_u64 v[4:5], s[6:7], 0, v[118:119]
	flat_load_dwordx4 v[82:85], v[4:5]
	flat_load_dwordx4 v[86:89], v[2:3]
	flat_load_dwordx4 v[90:93], v[2:3] offset:32
	flat_load_dwordx4 v[94:97], v[2:3] offset:64
	flat_load_dwordx4 v[98:101], v[2:3] offset:96
	flat_load_dwordx4 v[102:105], v[2:3] offset:128
	flat_load_dwordx4 v[106:109], v[2:3] offset:160
	s_add_u32 s14, s4, 0x3000
	s_addc_u32 s15, s5, 0
	global_load_dwordx4 v[176:179], v0, s[14:15]
	global_load_dwordx4 v[180:183], v112, s[14:15]
	global_load_dwordx4 v[184:187], v114, s[14:15]
	s_mov_b32 s0, 0x2aaaaaab
	v_mul_hi_i32 v5, v8, s0
	v_add_u32_e32 v6, 0x100, v8
	v_add_u32_e32 v7, 0x200, v8
	v_lshrrev_b32_e32 v11, 31, v5
	v_ashrrev_i32_e32 v5, 1, v5
	v_mul_hi_i32 v12, v6, s0
	v_and_b32_e32 v9, 0xffffffe0, v9
	v_mul_hi_i32 v13, v7, s0
	v_add_u32_e32 v2, v5, v11
	v_lshrrev_b32_e32 v3, 31, v12
	v_ashrrev_i32_e32 v5, 1, v12
	s_movk_i32 s0, 0x68
	v_add_u32_e32 v125, s94, v9
	v_lshrrev_b32_e32 v9, 31, v13
	v_ashrrev_i32_e32 v11, 1, v13
	v_mul_lo_u32 v12, v2, 12
	v_mul_lo_u32 v2, v2, s0
	v_add_u32_e32 v3, v5, v3
	v_add_u32_e32 v5, v11, v9
	v_sub_u32_e32 v9, v8, v12
	v_lshlrev_b32_e32 v127, 1, v2
	v_mul_lo_u32 v2, v3, 12
	v_mul_lo_u32 v3, v3, s0
	v_lshlrev_b32_e32 v11, 3, v9
	v_lshlrev_b32_e32 v9, 4, v9
	v_sub_u32_e32 v2, v6, v2
	v_lshlrev_b32_e32 v128, 1, v3
	v_add3_u32 v3, s33, v127, v9
	v_lshlrev_b32_e32 v9, 3, v2
	v_lshlrev_b32_e32 v2, 4, v2
	v_add3_u32 v2, s33, v128, v2
	s_waitcnt lgkmcnt(0)
	s_barrier
	v_and_b32_e32 v4, 31, v8
	v_lshlrev_b32_e32 v10, 3, v121
	s_waitcnt vmcnt(0)
	ds_write_b128 v3, v[66:69]
	ds_write_b128 v2, v[70:73]
	v_mul_lo_u32 v2, v5, 12
	v_sub_u32_e32 v2, v7, v2
	v_mul_lo_u32 v5, v5, s0
	v_lshlrev_b32_e32 v3, 3, v2
	v_lshlrev_b32_e32 v129, 1, v5
	v_lshlrev_b32_e32 v2, 4, v2
	v_add3_u32 v2, s33, v129, v2
	ds_write_b128 v2, v[74:77]
	v_lshrrev_b32_e32 v2, 3, v8
	v_lshlrev_b32_e32 v5, 3, v8
	s_movk_i32 s0, 0x48
	v_and_b32_e32 v5, 56, v5
	v_mul_lo_u32 v2, v2, s0
	v_lshlrev_b32_e32 v130, 1, v2
	v_lshlrev_b32_e32 v131, 1, v5
	v_and_b32_e32 v217, 1, v215
	v_lshlrev_b32_e32 v217, 3, v217
	v_sub_u32_e32 v217, v131, v217
	v_add_u32_e32 v217, 0x3400, v217
	v_add3_u32 v2, s33, v130, v217
	ds_write2_b64 v2, v[78:79], v[80:81] offset1:2
	v_lshrrev_b32_e32 v2, 3, v6
	v_mul_lo_u32 v2, v2, s0
	v_lshlrev_b32_e32 v132, 1, v2
	v_add3_u32 v2, s33, v132, v217
	v_mov_b32_e32 v18, v1
	v_mov_b32_e32 v19, v1
	v_or_b32_e32 v126, v125, v4
	ds_write2_b64 v2, v[82:83], v[84:85] offset1:2
	v_mul_u32_u24_e32 v134, 0xd0, v4
	v_mul_u32_u24_e32 v136, 0x90, v4
	v_mov_b32_e32 v20, v1
	v_mov_b32_e32 v21, v1
	v_mov_b32_e32 v22, v1
	v_mov_b32_e32 v23, v1
	v_mov_b32_e32 v24, v1
	v_mov_b32_e32 v25, v1
	v_mov_b32_e32 v26, v1
	v_mov_b32_e32 v27, v1
	v_mov_b32_e32 v28, v1
	v_mov_b32_e32 v29, v1
	v_mov_b32_e32 v30, v1
	v_mov_b32_e32 v31, v1
	v_mov_b32_e32 v32, v1
	v_mov_b32_e32 v33, v1
	v_lshlrev_b32_e32 v137, 1, v10
	v_lshlrev_b32_e32 v138, 1, v11
	v_lshlrev_b32_e32 v139, 1, v9
	v_lshlrev_b32_e32 v140, 1, v3
	v_mov_b64_e32 v[2:3], v[18:19]
	s_mov_b32 s95, s49
	v_ashrrev_i32_e32 v111, 31, v110
	v_or_b32_e32 v133, 31, v125
	v_lshlrev_b32_e32 v123, 2, v121
	s_mov_b32 s16, 0
	v_mov_b32_e32 v135, 0
	v_mov_b32_e32 v122, 0xff800000
	s_mov_b32 s12, 0
	v_mov_b64_e32 v[4:5], v[20:21]
	v_mov_b64_e32 v[6:7], v[22:23]
	v_mov_b64_e32 v[8:9], v[24:25]
	v_mov_b64_e32 v[10:11], v[26:27]
	v_mov_b64_e32 v[12:13], v[28:29]
	v_mov_b64_e32 v[14:15], v[30:31]
	v_mov_b64_e32 v[16:17], v[32:33]
	v_add3_u32 v127, s33, v127, v138
	v_add3_u32 v128, s33, v128, v139
	v_add3_u32 v129, s33, v129, v140
	v_add3_u32 v130, s33, v130, v217
	v_add3_u32 v132, s33, v132, v217
	v_add_u32_e32 v138, 0x5900, v130
	v_add_u32_e32 v139, 0x5900, v132
	v_add3_u32 v216, s33, v134, v137
	v_lshlrev_b32_e32 v231, 2, v123
	v_add3_u32 v231, s33, v136, v231
	ds_write_b128 v127, v[176:179] offset:22784
	ds_write_b128 v128, v[180:183] offset:22784
	ds_write_b128 v129, v[184:187] offset:22784
	s_waitcnt lgkmcnt(0)
	s_barrier
	ds_read_b128 v[208:211], v216 offset:0
	ds_read_b128 v[232:235], v216 offset:6656
	ds_read_b128 v[236:239], v216 offset:32
	ds_read_b128 v[240:243], v216 offset:6688
	ds_read_b128 v[244:247], v216 offset:64
	ds_read_b128 v[248:251], v216 offset:6720
	s_waitcnt lgkmcnt(4)
	v_mfma_f32_32x32x16_bf16 v[50:65], v[208:211], v[86:89], 0
	v_mfma_f32_32x32x16_bf16 v[34:49], v[232:235], v[86:89], 0
	ds_read_b128 v[208:211], v216 offset:96
	ds_read_b128 v[232:235], v216 offset:6752
	s_waitcnt lgkmcnt(4)
	v_mfma_f32_32x32x16_bf16 v[50:65], v[236:239], v[90:93], v[50:65]
	v_mfma_f32_32x32x16_bf16 v[34:49], v[240:243], v[90:93], v[34:49]
	ds_read_b128 v[236:239], v216 offset:128
	ds_read_b128 v[240:243], v216 offset:6784
	s_waitcnt lgkmcnt(4)
	v_mfma_f32_32x32x16_bf16 v[50:65], v[244:247], v[94:97], v[50:65]
	v_mfma_f32_32x32x16_bf16 v[34:49], v[248:251], v[94:97], v[34:49]
	ds_read_b128 v[244:247], v216 offset:160
	ds_read_b128 v[248:251], v216 offset:6816
	s_waitcnt lgkmcnt(4)
	v_mfma_f32_32x32x16_bf16 v[50:65], v[208:211], v[98:101], v[50:65]
	v_mfma_f32_32x32x16_bf16 v[34:49], v[232:235], v[98:101], v[34:49]
	s_waitcnt lgkmcnt(2)
	v_mfma_f32_32x32x16_bf16 v[50:65], v[236:239], v[102:105], v[50:65]
	v_mfma_f32_32x32x16_bf16 v[34:49], v[240:243], v[102:105], v[34:49]
	s_waitcnt lgkmcnt(0)
	v_mfma_f32_32x32x16_bf16 v[50:65], v[244:247], v[106:109], v[50:65]
	v_mfma_f32_32x32x16_bf16 v[34:49], v[248:251], v[106:109], v[34:49]
	s_nop 7
	s_nop 3
;     ...
;     for (int it = 0; it < ntiles; ++it) {
;         const int kt = DESC ? ntiles - 1 - it : it, buf = it & 1;
;         if (it + 1 < ntiles) ld_tile(DESC ? kt - 1 : kt + 1);
;         __syncthreads();
;         if ((MODE == 1 || (MODE == 0 && DESC)) && it > 0) {
;             const int* fl = (const int*)(smem0 + SMEM_FLAG) + ((it - 1) & 1) * 8;
;             if ((fl[0] & fl[1] & fl[2] & fl[3] & fl[4] & fl[5] & fl[6] & fl[7]) != 0) break;
;         }
;         const bf16_t* sK = (const bf16_t*)(smem + buf * ATT_BUF); const bf16_t* sV = (const bf16_t*)(smem + buf * ATT_BUF + 13312);
;         const float* sC = (const float*)(smem + buf * ATT_BUF + 22528);
;         bool active = true;
;         if (MODE == 0) active = (64 * kt <= q0 + 32 * w + 31);
;         if (MODE == 1) active = (64 * kt < q0 + 32 * w + 31);
;         if (active) {
;             f32x16 sc[2];
; #pragma unroll
;             for (int i = 0; i < 16; ++i) { sc[0][i] = 0.f; sc[1][i] = 0.f; }
; #pragma unroll
;             for (int s = 0; s < NKS; ++s) {
;                 const bf16x8 k0 = *(const bf16x8*)(sK + r * KS + 16 * s + 8 * h), k1 = *(const bf16x8*)(sK + (32 + r) * KS + 16 * s + 8 * h);
;                 sc[0] = MFMA32(k0, qf[s], sc[0]);
;                 sc[1] = MFMA32(k1, qf[s], sc[1]);
;             }
;     ...
;                 if (MODE == 0 && (64 * kt + 63 > q0 + 32 * w)) {
; #pragma unroll
;                     for (int mt = 0; mt < 2; ++mt)
; #pragma unroll
;                         for (int qd = 0; qd < 4; ++qd)
; #pragma unroll
;                             for (int e = 0; e < 4; ++e)
;                                 if (64 * kt + 32 * mt + 8 * qd + 4 * h + e > qidx) s4[mt][qd][e] = -INFINITY;
;                 }
;                 float mx = fmaxf(s4[0][0].x, s4[1][0].x);
; #pragma unroll
;                 for (int qd = 0; qd < 4; ++qd) {
;                     mx = fmaxf(fmaxf(mx, s4[0][qd].y), s4[1][qd].y);
;                     mx = fmaxf(fmaxf(mx, s4[0][qd].z), s4[1][qd].z);
;                     mx = fmaxf(fmaxf(mx, s4[0][qd].w), s4[1][qd].w);
;                     if (qd < 3) mx = fmaxf(fmaxf(mx, s4[0][qd + 1].x), s4[1][qd + 1].x);
;                 }
;                 mx = xhalf_max(mx);
;                 const float mn = fmaxf(m, mx), alpha = fexp2(m - mn);
;                 m = mn;
;                 f32x4 ps4 = {0.f, 0.f, 0.f, 0.f};
;                 const float nmn = -mn;
.Lm3_even:
	s_add_i32 s17, s12, 2
	s_add_i32 s48, s16, 64
	s_lshl_b64 s[14:15], s[48:49], 1
	s_add_u32 s14, s6, s14
	s_addc_u32 s15, s7, s15
	global_load_dwordx4 v[78:81], v116, s[14:15]
	global_load_dwordx4 v[82:85], v118, s[14:15]
	s_cmp_ge_u32 s17, s66
	s_cbranch_scc1 .Lm3_even_nok
	s_add_i32 s48, s16, 0x80
	s_mul_i32 s14, s48, 0xc0
	s_mul_hi_u32 s13, s48, 0xc0
	s_add_u32 s14, s4, s14
	s_addc_u32 s15, s5, s13
	global_load_dwordx4 v[66:69], v0, s[14:15]
	global_load_dwordx4 v[70:73], v112, s[14:15]
	global_load_dwordx4 v[74:77], v114, s[14:15]
.Lm3_even_nok:
	s_waitcnt lgkmcnt(0)
	s_barrier
	ds_read_b128 v[208:211], v216 offset:22784
	ds_read_b128 v[232:235], v216 offset:29440
	ds_read_b128 v[236:239], v216 offset:22816
	ds_read_b128 v[240:243], v216 offset:29472
	ds_read_b128 v[244:247], v216 offset:22848
	ds_read_b128 v[248:251], v216 offset:29504
	s_add_i32 s14, s16, 63
	v_cmp_gt_i32_e32 vcc, s14, v125
	s_and_saveexec_b64 s[14:15], vcc
	s_cbranch_execz .Lm3_nomask_e
	v_sub_u32_e32 v213, v126, v123
	v_subrev_u32_e32 v213, s16, v213
	v_cmp_le_i32_e32 vcc, 0, v213
	s_nop 1
	v_cndmask_b32_e32 v50, v228, v50, vcc
	v_cmp_le_i32_e32 vcc, 1, v213
	s_nop 1
	v_cndmask_b32_e32 v51, v228, v51, vcc
	v_cmp_le_i32_e32 vcc, 2, v213
	s_nop 1
	v_cndmask_b32_e32 v52, v228, v52, vcc
	v_cmp_le_i32_e32 vcc, 3, v213
	s_nop 1
	v_cndmask_b32_e32 v53, v228, v53, vcc
	v_cmp_le_i32_e32 vcc, 8, v213
	s_nop 1
	v_cndmask_b32_e32 v54, v228, v54, vcc
	v_cmp_le_i32_e32 vcc, 9, v213
	s_nop 1
	v_cndmask_b32_e32 v55, v228, v55, vcc
	v_cmp_le_i32_e32 vcc, 10, v213
	s_nop 1
	v_cndmask_b32_e32 v56, v228, v56, vcc
	v_cmp_le_i32_e32 vcc, 11, v213
	s_nop 1
	v_cndmask_b32_e32 v57, v228, v57, vcc
	v_cmp_le_i32_e32 vcc, 16, v213
	s_nop 1
	v_cndmask_b32_e32 v58, v228, v58, vcc
	v_cmp_le_i32_e32 vcc, 17, v213
	s_nop 1
	v_cndmask_b32_e32 v59, v228, v59, vcc
	v_cmp_le_i32_e32 vcc, 18, v213
	s_nop 1
	v_cndmask_b32_e32 v60, v228, v60, vcc
	v_cmp_le_i32_e32 vcc, 19, v213
	s_nop 1
	v_cndmask_b32_e32 v61, v228, v61, vcc
	v_cmp_le_i32_e32 vcc, 24, v213
	s_nop 1
	v_cndmask_b32_e32 v62, v228, v62, vcc
	v_cmp_le_i32_e32 vcc, 25, v213
	s_nop 1
	v_cndmask_b32_e32 v63, v228, v63, vcc
	v_cmp_le_i32_e32 vcc, 26, v213
	s_nop 1
	v_cndmask_b32_e32 v64, v228, v64, vcc
	v_cmp_le_i32_e32 vcc, 27, v213
	s_nop 1
	v_cndmask_b32_e32 v65, v228, v65, vcc
	v_cmp_le_i32_e32 vcc, 32, v213
	s_nop 1
	v_cndmask_b32_e32 v34, v228, v34, vcc
	v_cmp_le_i32_e32 vcc, 33, v213
	s_nop 1
	v_cndmask_b32_e32 v35, v228, v35, vcc
	v_cmp_le_i32_e32 vcc, 34, v213
	s_nop 1
	v_cndmask_b32_e32 v36, v228, v36, vcc
	v_cmp_le_i32_e32 vcc, 35, v213
	s_nop 1
	v_cndmask_b32_e32 v37, v228, v37, vcc
	v_cmp_le_i32_e32 vcc, 40, v213
	s_nop 1
	v_cndmask_b32_e32 v38, v228, v38, vcc
	v_cmp_le_i32_e32 vcc, 41, v213
	s_nop 1
	v_cndmask_b32_e32 v39, v228, v39, vcc
	v_cmp_le_i32_e32 vcc, 42, v213
	s_nop 1
	v_cndmask_b32_e32 v40, v228, v40, vcc
	v_cmp_le_i32_e32 vcc, 43, v213
	s_nop 1
	v_cndmask_b32_e32 v41, v228, v41, vcc
	v_cmp_le_i32_e32 vcc, 48, v213
	s_nop 1
	v_cndmask_b32_e32 v42, v228, v42, vcc
	v_cmp_le_i32_e32 vcc, 49, v213
	s_nop 1
	v_cndmask_b32_e32 v43, v228, v43, vcc
	v_cmp_le_i32_e32 vcc, 50, v213
	s_nop 1
	v_cndmask_b32_e32 v44, v228, v44, vcc
	v_cmp_le_i32_e32 vcc, 51, v213
	s_nop 1
	v_cndmask_b32_e32 v45, v228, v45, vcc
	v_cmp_le_i32_e32 vcc, 56, v213
	s_nop 1
	v_cndmask_b32_e32 v46, v228, v46, vcc
	v_cmp_le_i32_e32 vcc, 57, v213
	s_nop 1
	v_cndmask_b32_e32 v47, v228, v47, vcc
	v_cmp_le_i32_e32 vcc, 58, v213
	s_nop 1
	v_cndmask_b32_e32 v48, v228, v48, vcc
	v_cmp_le_i32_e32 vcc, 59, v213
	s_nop 1
	v_cndmask_b32_e32 v49, v228, v49, vcc
.Lm3_nomask_e:
	s_or_b64 exec, exec, s[14:15]
	v_max3_f32 v120, v50, v51, v52
	v_max3_f32 v141, v53, v54, v55
	v_max3_f32 v154, v56, v57, v58
	v_max3_f32 v212, v59, v60, v61
	v_max3_f32 v120, v120, v62, v63
	v_max3_f32 v141, v141, v64, v65
	v_max3_f32 v154, v154, v34, v35
	v_max3_f32 v212, v212, v36, v37
	s_waitcnt lgkmcnt(4)
	v_mfma_f32_32x32x16_bf16 v[176:191], v[208:211], v[86:89], 0
	v_mfma_f32_32x32x16_bf16 v[192:207], v[232:235], v[86:89], 0
	ds_read_b128 v[208:211], v216 offset:22880
	ds_read_b128 v[232:235], v216 offset:29536
	v_max3_f32 v120, v120, v38, v39
	v_max3_f32 v141, v141, v40, v41
	v_max3_f32 v154, v154, v42, v43
	v_max3_f32 v212, v212, v44, v45
	v_max3_f32 v120, v120, v46, v47
	v_max3_f32 v141, v141, v48, v49
	v_max3_f32 v120, v120, v141, v154
	v_max_f32_e32 v120, v120, v212
	s_waitcnt lgkmcnt(4)
	v_mfma_f32_32x32x16_bf16 v[176:191], v[236:239], v[90:93], v[176:191]
	v_mfma_f32_32x32x16_bf16 v[192:207], v[240:243], v[90:93], v[192:207]
	ds_read_b128 v[236:239], v216 offset:22912
	ds_read_b128 v[240:243], v216 offset:29568
	v_mov_b32_e32 v141, v120
	s_nop 1
	v_permlane32_swap_b32_e32 v120, v141
	v_max3_f32 v120, v122, v120, v141
	v_sub_f32_e32 v122, v122, v120
	v_exp_f32_e32 v122, v122
	s_waitcnt lgkmcnt(4)
	v_mfma_f32_32x32x16_bf16 v[176:191], v[244:247], v[94:97], v[176:191]
	v_mfma_f32_32x32x16_bf16 v[192:207], v[248:251], v[94:97], v[192:207]
	ds_read_b128 v[244:247], v216 offset:22944
	ds_read_b128 v[248:251], v216 offset:29600
	v_cmp_neq_f32_e32 vcc, 1.0, v122
	s_cbranch_vccz .Lm3_noresc_e
	v_pk_mul_f32 v[32:33], v[32:33], v[122:123] op_sel_hi:[1,0]
	v_pk_mul_f32 v[30:31], v[30:31], v[122:123] op_sel_hi:[1,0]
	v_pk_mul_f32 v[28:29], v[28:29], v[122:123] op_sel_hi:[1,0]
	v_pk_mul_f32 v[26:27], v[26:27], v[122:123] op_sel_hi:[1,0]
	v_pk_mul_f32 v[24:25], v[24:25], v[122:123] op_sel_hi:[1,0]
	v_pk_mul_f32 v[22:23], v[22:23], v[122:123] op_sel_hi:[1,0]
	v_pk_mul_f32 v[20:21], v[20:21], v[122:123] op_sel_hi:[1,0]
	v_pk_mul_f32 v[18:19], v[18:19], v[122:123] op_sel_hi:[1,0]
	v_pk_mul_f32 v[16:17], v[16:17], v[122:123] op_sel_hi:[1,0]
	v_pk_mul_f32 v[14:15], v[14:15], v[122:123] op_sel_hi:[1,0]
	v_pk_mul_f32 v[12:13], v[12:13], v[122:123] op_sel_hi:[1,0]
	v_pk_mul_f32 v[10:11], v[10:11], v[122:123] op_sel_hi:[1,0]
	v_pk_mul_f32 v[8:9], v[8:9], v[122:123] op_sel_hi:[1,0]
	v_pk_mul_f32 v[6:7], v[6:7], v[122:123] op_sel_hi:[1,0]
	v_pk_mul_f32 v[4:5], v[4:5], v[122:123] op_sel_hi:[1,0]
	v_pk_mul_f32 v[2:3], v[2:3], v[122:123] op_sel_hi:[1,0]
; #define MFMA32(a, b, c) __builtin_amdgcn_mfma_f32_32x32x16_bf16((a), (b), (c), 0, 0, 0)
;     ...
;     auto st_tile = [&](int buf) {
;         bf16_t* sK = (bf16_t*)(smem + buf * ATT_BUF); bf16_t* sV = (bf16_t*)(smem + buf * ATT_BUF + 13312); float* sC = (float*)(smem + buf * ATT_BUF + 22528);
; #pragma unroll
;         for (int j = 0; j < NKL; ++j) { const int c = tid + 256 * j, row = c / KCH, kc = (c % KCH) * 8; *(u32x4*)(sK + row * KS + kc) = rk[j]; }
; #pragma unroll
;         for (int j = 0; j < 2; ++j) { const int c = tid + 256 * j, row = c >> 3, kc = (c & 7) * 8; *(u32x4*)(sV + row * LS + kc) = rv[j]; }
;         if (cdec && tid < 16) *(f32x4*)(sC + 4 * tid) = rc;
;     };
;     ...
;                 const float mn = fmaxf(m, mx), alpha = fexp2(m - mn);
;                 m = mn;
;                 f32x4 ps4 = {0.f, 0.f, 0.f, 0.f};
;                 const float nmn = -mn;
;                 const f32x4 nm4 = {nmn, nmn, nmn, nmn};
;                 if (__builtin_amdgcn_ballot_w64(alpha != 1.f) != 0) { o0 *= alpha; o1 *= alpha; }
; #pragma unroll
;                 for (int s2 = 0; s2 < 4; ++s2) {
;                     const int mt = s2 >> 1, s = s2 & 1;
;                     f32x4 da = s4[mt][2 * s] + nm4, db = s4[mt][2 * s + 1] + nm4;
;                     da.x = fexp2(da.x); da.y = fexp2(da.y); da.z = fexp2(da.z); da.w = fexp2(da.w);
;                     db.x = fexp2(db.x); db.y = fexp2(db.y); db.z = fexp2(db.z); db.w = fexp2(db.w);
;                     ps4 += da; ps4 += db;
;                     u32x4 pp;
;                     pp.x = pk2(da.x, da.y); pp.y = pk2(da.z, da.w); pp.z = pk2(db.x, db.y); pp.w = pk2(db.z, db.w);
;                     const bf16x8 pfr = __builtin_bit_cast(bf16x8, pp);
;                     const s16x4 a0 = *(const s16x4*)(sV + r * LS + 16 * s2 + 4 * h), a1 = *(const s16x4*)(sV + r * LS + 16 * s2 + 8 + 4 * h);
;                     const s16x4 b0 = *(const s16x4*)(sV + (32 + r) * LS + 16 * s2 + 4 * h), b1 = *(const s16x4*)(sV + (32 + r) * LS + 16 * s2 + 8 + 4 * h);
;                     const bf16x8 v0 = __builtin_shufflevector(a0, a1, 0, 1, 2, 3, 4, 5, 6, 7), v1 = __builtin_shufflevector(b0, b1, 0, 1, 2, 3, 4, 5, 6, 7);
;                     o0 = MFMA32(v0, pfr, o0);
;                     o1 = MFMA32(v1, pfr, o1);
;                 }
;                 lsum = lsum * alpha + ((ps4.x + ps4.y) + (ps4.z + ps4.w));
.Lm3_noresc_e:
	v_sub_f32_e32 v50, v50, v120
	v_sub_f32_e32 v51, v51, v120
	v_sub_f32_e32 v52, v52, v120
	v_sub_f32_e32 v53, v53, v120
	v_sub_f32_e32 v54, v54, v120
	v_sub_f32_e32 v55, v55, v120
	v_sub_f32_e32 v56, v56, v120
	v_sub_f32_e32 v57, v57, v120
	s_waitcnt lgkmcnt(4)
	v_mfma_f32_32x32x16_bf16 v[176:191], v[208:211], v[98:101], v[176:191]
	v_mfma_f32_32x32x16_bf16 v[192:207], v[232:235], v[98:101], v[192:207]
	ds_read_b128 v[208:211], v231 offset:13312
	ds_read_b128 v[232:235], v231 offset:17920
	v_exp_f32_e32 v50, v50
	v_exp_f32_e32 v51, v51
	v_exp_f32_e32 v52, v52
	v_exp_f32_e32 v53, v53
	s_waitcnt lgkmcnt(4)
	v_mfma_f32_32x32x16_bf16 v[176:191], v[236:239], v[102:105], v[176:191]
	v_mfma_f32_32x32x16_bf16 v[192:207], v[240:243], v[102:105], v[192:207]
	ds_read_b128 v[236:239], v231 offset:13344
	ds_read_b128 v[240:243], v231 offset:17952
	v_exp_f32_e32 v54, v54
	v_exp_f32_e32 v55, v55
	v_exp_f32_e32 v56, v56
	v_exp_f32_e32 v57, v57
	s_waitcnt lgkmcnt(4)
	v_mfma_f32_32x32x16_bf16 v[176:191], v[244:247], v[106:109], v[176:191]
	v_mfma_f32_32x32x16_bf16 v[192:207], v[248:251], v[106:109], v[192:207]
	ds_read_b128 v[244:247], v231 offset:13376
	ds_read_b128 v[248:251], v231 offset:17984
	v_cvt_pk_bf16_f32 v142, v50, v51
	v_cvt_pk_bf16_f32 v143, v52, v53
	v_cvt_pk_bf16_f32 v144, v54, v55
	v_cvt_pk_bf16_f32 v145, v56, v57
	v_sub_f32_e32 v58, v58, v120
	v_sub_f32_e32 v59, v59, v120
	v_sub_f32_e32 v60, v60, v120
	v_sub_f32_e32 v61, v61, v120
	v_sub_f32_e32 v62, v62, v120
	v_sub_f32_e32 v63, v63, v120
	v_sub_f32_e32 v64, v64, v120
	v_sub_f32_e32 v65, v65, v120
	s_waitcnt lgkmcnt(4)
	v_mfma_f32_32x32x16_bf16 v[18:33], v[208:211], v[142:145], v[18:33]
	v_mfma_f32_32x32x16_bf16 v[2:17], v[232:235], v[142:145], v[2:17]
	ds_read_b128 v[208:211], v231 offset:13408
	ds_read_b128 v[232:235], v231 offset:18016
	v_exp_f32_e32 v58, v58
	v_exp_f32_e32 v59, v59
	v_exp_f32_e32 v60, v60
	v_exp_f32_e32 v61, v61
	v_exp_f32_e32 v62, v62
	v_exp_f32_e32 v63, v63
	v_exp_f32_e32 v64, v64
	v_exp_f32_e32 v65, v65
	v_add_f32_e32 v141, v50, v51
	v_add_f32_e32 v154, v52, v53
	v_add_f32_e32 v212, v54, v55
	v_add_f32_e32 v213, v56, v57
	v_add_f32_e32 v141, v141, v154
	v_add_f32_e32 v212, v212, v213
	v_add_f32_e32 v230, v141, v212
	v_cvt_pk_bf16_f32 v146, v58, v59
	v_cvt_pk_bf16_f32 v147, v60, v61
	v_cvt_pk_bf16_f32 v148, v62, v63
	v_cvt_pk_bf16_f32 v149, v64, v65
	v_sub_f32_e32 v34, v34, v120
	v_sub_f32_e32 v35, v35, v120
	v_sub_f32_e32 v36, v36, v120
	v_sub_f32_e32 v37, v37, v120
	v_sub_f32_e32 v38, v38, v120
	v_sub_f32_e32 v39, v39, v120
	v_sub_f32_e32 v40, v40, v120
	v_sub_f32_e32 v41, v41, v120
	s_waitcnt lgkmcnt(4)
	v_mfma_f32_32x32x16_bf16 v[18:33], v[236:239], v[146:149], v[18:33]
	v_mfma_f32_32x32x16_bf16 v[2:17], v[240:243], v[146:149], v[2:17]
	v_exp_f32_e32 v34, v34
	v_exp_f32_e32 v35, v35
	v_exp_f32_e32 v36, v36
	v_exp_f32_e32 v37, v37
	v_exp_f32_e32 v38, v38
	v_exp_f32_e32 v39, v39
	v_exp_f32_e32 v40, v40
	v_exp_f32_e32 v41, v41
	v_add_f32_e32 v141, v58, v59
	v_add_f32_e32 v154, v60, v61
	v_add_f32_e32 v212, v62, v63
	v_add_f32_e32 v213, v64, v65
	v_add_f32_e32 v141, v141, v154
	v_add_f32_e32 v212, v212, v213
	v_add_f32_e32 v141, v141, v212
	v_add_f32_e32 v230, v230, v141
	v_cvt_pk_bf16_f32 v150, v34, v35
	v_cvt_pk_bf16_f32 v151, v36, v37
	v_cvt_pk_bf16_f32 v152, v38, v39
	v_cvt_pk_bf16_f32 v153, v40, v41
	v_sub_f32_e32 v42, v42, v120
	v_sub_f32_e32 v43, v43, v120
	v_sub_f32_e32 v44, v44, v120
	v_sub_f32_e32 v45, v45, v120
	v_sub_f32_e32 v46, v46, v120
	v_sub_f32_e32 v47, v47, v120
	v_sub_f32_e32 v48, v48, v120
	v_sub_f32_e32 v49, v49, v120
	s_waitcnt lgkmcnt(2)
	v_mfma_f32_32x32x16_bf16 v[18:33], v[244:247], v[150:153], v[18:33]
	v_mfma_f32_32x32x16_bf16 v[2:17], v[248:251], v[150:153], v[2:17]
	v_exp_f32_e32 v42, v42
	v_exp_f32_e32 v43, v43
	v_exp_f32_e32 v44, v44
	v_exp_f32_e32 v45, v45
	v_exp_f32_e32 v46, v46
	v_exp_f32_e32 v47, v47
	v_exp_f32_e32 v48, v48
	v_exp_f32_e32 v49, v49
	v_add_f32_e32 v141, v34, v35
	v_add_f32_e32 v154, v36, v37
	v_add_f32_e32 v212, v38, v39
	v_add_f32_e32 v213, v40, v41
	v_add_f32_e32 v141, v141, v154
	v_add_f32_e32 v212, v212, v213
	v_add_f32_e32 v141, v141, v212
	v_add_f32_e32 v230, v230, v141
	v_cvt_pk_bf16_f32 v142, v42, v43
	v_cvt_pk_bf16_f32 v143, v44, v45
	v_cvt_pk_bf16_f32 v144, v46, v47
	v_cvt_pk_bf16_f32 v145, v48, v49
	v_add_f32_e32 v141, v42, v43
	v_add_f32_e32 v154, v44, v45
	v_add_f32_e32 v212, v46, v47
	v_add_f32_e32 v213, v48, v49
	s_waitcnt lgkmcnt(0)
	v_mfma_f32_32x32x16_bf16 v[18:33], v[208:211], v[142:145], v[18:33]
	v_mfma_f32_32x32x16_bf16 v[2:17], v[232:235], v[142:145], v[2:17]
	v_add_f32_e32 v141, v141, v154
	v_add_f32_e32 v212, v212, v213
	v_add_f32_e32 v141, v141, v212
	v_add_f32_e32 v230, v230, v141
	v_fma_f32 v135, v135, v122, v230
	v_mov_b32_e32 v122, v120
	s_waitcnt vmcnt(0)
	ds_write2_b64 v138, v[78:79], v[80:81] offset1:2
	ds_write2_b64 v139, v[82:83], v[84:85] offset1:2
	s_cmp_ge_u32 s17, s66
	s_cbranch_scc1 .Lm3_even_nokw
	ds_write_b128 v127, v[66:69]
	ds_write_b128 v128, v[70:73]
	ds_write_b128 v129, v[74:77]
;     ...
;         const bf16_t* sK = (const bf16_t*)(smem + buf * ATT_BUF); const bf16_t* sV = (const bf16_t*)(smem + buf * ATT_BUF + 13312);
;         const float* sC = (const float*)(smem + buf * ATT_BUF + 22528);
;     ...
;                 float mx = fmaxf(s4[0][0].x, s4[1][0].x);
; #pragma unroll
;                 for (int qd = 0; qd < 4; ++qd) {
;                     mx = fmaxf(fmaxf(mx, s4[0][qd].y), s4[1][qd].y);
;                     mx = fmaxf(fmaxf(mx, s4[0][qd].z), s4[1][qd].z);
;                     mx = fmaxf(fmaxf(mx, s4[0][qd].w), s4[1][qd].w);
;                     if (qd < 3) mx = fmaxf(fmaxf(mx, s4[0][qd + 1].x), s4[1][qd + 1].x);
;                 }
;                 mx = xhalf_max(mx);
;                 const float mn = fmaxf(m, mx), alpha = fexp2(m - mn);
;                 m = mn;
;                 f32x4 ps4 = {0.f, 0.f, 0.f, 0.f};
;                 const float nmn = -mn;
;                 const f32x4 nm4 = {nmn, nmn, nmn, nmn};
;                 if (__builtin_amdgcn_ballot_w64(alpha != 1.f) != 0) { o0 *= alpha; o1 *= alpha; }
; #pragma unroll
;                 for (int s2 = 0; s2 < 4; ++s2) {
;                     const int mt = s2 >> 1, s = s2 & 1;
;                     f32x4 da = s4[mt][2 * s] + nm4, db = s4[mt][2 * s + 1] + nm4;
;                     da.x = fexp2(da.x); da.y = fexp2(da.y); da.z = fexp2(da.z); da.w = fexp2(da.w);
;                     db.x = fexp2(db.x); db.y = fexp2(db.y); db.z = fexp2(db.z); db.w = fexp2(db.w);
;                     ps4 += da; ps4 += db;
;                     u32x4 pp;
;                     pp.x = pk2(da.x, da.y); pp.y = pk2(da.z, da.w); pp.z = pk2(db.x, db.y); pp.w = pk2(db.z, db.w);
;                     const bf16x8 pfr = __builtin_bit_cast(bf16x8, pp);
;                     const s16x4 a0 = *(const s16x4*)(sV + r * LS + 16 * s2 + 4 * h), a1 = *(const s16x4*)(sV + r * LS + 16 * s2 + 8 + 4 * h);
;                     const s16x4 b0 = *(const s16x4*)(sV + (32 + r) * LS + 16 * s2 + 4 * h), b1 = *(const s16x4*)(sV + (32 + r) * LS + 16 * s2 + 8 + 4 * h);
;                     const bf16x8 v0 = __builtin_shufflevector(a0, a1, 0, 1, 2, 3, 4, 5, 6, 7), v1 = __builtin_shufflevector(b0, b1, 0, 1, 2, 3, 4, 5, 6, 7);
;                     o0 = MFMA32(v0, pfr, o0);
;                     o1 = MFMA32(v1, pfr, o1);
;                 }
;                 lsum = lsum * alpha + ((ps4.x + ps4.y) + (ps4.z + ps4.w));
.Lm3_even_nokw:
	s_add_i32 s12, s12, 1
	s_add_i32 s16, s16, 64
	s_add_i32 s17, s12, 1
	s_cmp_ge_u32 s17, s66
	s_cbranch_scc1 .Lm3_final
	s_add_i32 s48, s16, 64
	s_lshl_b64 s[14:15], s[48:49], 1
	s_add_u32 s14, s6, s14
	s_addc_u32 s15, s7, s15
	global_load_dwordx4 v[78:81], v116, s[14:15]
	global_load_dwordx4 v[82:85], v118, s[14:15]
	s_add_i32 s48, s16, 0x80
	s_mul_i32 s14, s48, 0xc0
	s_mul_hi_u32 s13, s48, 0xc0
	s_add_u32 s14, s4, s14
	s_addc_u32 s15, s5, s13
	global_load_dwordx4 v[66:69], v0, s[14:15]
	global_load_dwordx4 v[70:73], v112, s[14:15]
	global_load_dwordx4 v[74:77], v114, s[14:15]
	s_waitcnt lgkmcnt(0)
	s_barrier
	ds_read_b128 v[208:211], v216 offset:0
	ds_read_b128 v[232:235], v216 offset:6656
	ds_read_b128 v[236:239], v216 offset:32
	ds_read_b128 v[240:243], v216 offset:6688
	ds_read_b128 v[244:247], v216 offset:64
	ds_read_b128 v[248:251], v216 offset:6720
	v_max3_f32 v120, v176, v177, v178
	v_max3_f32 v141, v179, v180, v181
	v_max3_f32 v154, v182, v183, v184
	v_max3_f32 v212, v185, v186, v187
	v_max3_f32 v120, v120, v188, v189
	v_max3_f32 v141, v141, v190, v191
	v_max3_f32 v154, v154, v192, v193
	v_max3_f32 v212, v212, v194, v195
	s_waitcnt lgkmcnt(4)
	v_mfma_f32_32x32x16_bf16 v[50:65], v[208:211], v[86:89], 0
	v_mfma_f32_32x32x16_bf16 v[34:49], v[232:235], v[86:89], 0
	ds_read_b128 v[208:211], v216 offset:96
	ds_read_b128 v[232:235], v216 offset:6752
	v_max3_f32 v120, v120, v196, v197
	v_max3_f32 v141, v141, v198, v199
	v_max3_f32 v154, v154, v200, v201
	v_max3_f32 v212, v212, v202, v203
	v_max3_f32 v120, v120, v204, v205
	v_max3_f32 v141, v141, v206, v207
	v_max3_f32 v120, v120, v141, v154
	v_max_f32_e32 v120, v120, v212
	s_waitcnt lgkmcnt(4)
	v_mfma_f32_32x32x16_bf16 v[50:65], v[236:239], v[90:93], v[50:65]
	v_mfma_f32_32x32x16_bf16 v[34:49], v[240:243], v[90:93], v[34:49]
	ds_read_b128 v[236:239], v216 offset:128
	ds_read_b128 v[240:243], v216 offset:6784
	v_mov_b32_e32 v141, v120
	s_nop 1
	v_permlane32_swap_b32_e32 v120, v141
	v_max3_f32 v120, v122, v120, v141
	v_sub_f32_e32 v122, v122, v120
	v_exp_f32_e32 v122, v122
	s_waitcnt lgkmcnt(4)
	v_mfma_f32_32x32x16_bf16 v[50:65], v[244:247], v[94:97], v[50:65]
	v_mfma_f32_32x32x16_bf16 v[34:49], v[248:251], v[94:97], v[34:49]
	ds_read_b128 v[244:247], v216 offset:160
	ds_read_b128 v[248:251], v216 offset:6816
	v_cmp_neq_f32_e32 vcc, 1.0, v122
	s_cbranch_vccz .Lm3_noresc_o
	v_pk_mul_f32 v[32:33], v[32:33], v[122:123] op_sel_hi:[1,0]
	v_pk_mul_f32 v[30:31], v[30:31], v[122:123] op_sel_hi:[1,0]
	v_pk_mul_f32 v[28:29], v[28:29], v[122:123] op_sel_hi:[1,0]
	v_pk_mul_f32 v[26:27], v[26:27], v[122:123] op_sel_hi:[1,0]
	v_pk_mul_f32 v[24:25], v[24:25], v[122:123] op_sel_hi:[1,0]
	v_pk_mul_f32 v[22:23], v[22:23], v[122:123] op_sel_hi:[1,0]
	v_pk_mul_f32 v[20:21], v[20:21], v[122:123] op_sel_hi:[1,0]
	v_pk_mul_f32 v[18:19], v[18:19], v[122:123] op_sel_hi:[1,0]
	v_pk_mul_f32 v[16:17], v[16:17], v[122:123] op_sel_hi:[1,0]
	v_pk_mul_f32 v[14:15], v[14:15], v[122:123] op_sel_hi:[1,0]
	v_pk_mul_f32 v[12:13], v[12:13], v[122:123] op_sel_hi:[1,0]
	v_pk_mul_f32 v[10:11], v[10:11], v[122:123] op_sel_hi:[1,0]
	v_pk_mul_f32 v[8:9], v[8:9], v[122:123] op_sel_hi:[1,0]
	v_pk_mul_f32 v[6:7], v[6:7], v[122:123] op_sel_hi:[1,0]
	v_pk_mul_f32 v[4:5], v[4:5], v[122:123] op_sel_hi:[1,0]
	v_pk_mul_f32 v[2:3], v[2:3], v[122:123] op_sel_hi:[1,0]
.Lm3_noresc_o:
	v_sub_f32_e32 v176, v176, v120
	v_sub_f32_e32 v177, v177, v120
	v_sub_f32_e32 v178, v178, v120
	v_sub_f32_e32 v179, v179, v120
	v_sub_f32_e32 v180, v180, v120
	v_sub_f32_e32 v181, v181, v120
	v_sub_f32_e32 v182, v182, v120
	v_sub_f32_e32 v183, v183, v120
	s_waitcnt lgkmcnt(4)
	v_mfma_f32_32x32x16_bf16 v[50:65], v[208:211], v[98:101], v[50:65]
	v_mfma_f32_32x32x16_bf16 v[34:49], v[232:235], v[98:101], v[34:49]
	ds_read_b128 v[208:211], v231 offset:36096
	ds_read_b128 v[232:235], v231 offset:40704
	v_exp_f32_e32 v176, v176
	v_exp_f32_e32 v177, v177
	v_exp_f32_e32 v178, v178
	v_exp_f32_e32 v179, v179
	s_waitcnt lgkmcnt(4)
	v_mfma_f32_32x32x16_bf16 v[50:65], v[236:239], v[102:105], v[50:65]
	v_mfma_f32_32x32x16_bf16 v[34:49], v[240:243], v[102:105], v[34:49]
	ds_read_b128 v[236:239], v231 offset:36128
	ds_read_b128 v[240:243], v231 offset:40736
	v_exp_f32_e32 v180, v180
	v_exp_f32_e32 v181, v181
	v_exp_f32_e32 v182, v182
	v_exp_f32_e32 v183, v183
	s_waitcnt lgkmcnt(4)
	v_mfma_f32_32x32x16_bf16 v[50:65], v[244:247], v[106:109], v[50:65]
	v_mfma_f32_32x32x16_bf16 v[34:49], v[248:251], v[106:109], v[34:49]
	ds_read_b128 v[244:247], v231 offset:36160
	ds_read_b128 v[248:251], v231 offset:40768
	v_cvt_pk_bf16_f32 v142, v176, v177
	v_cvt_pk_bf16_f32 v143, v178, v179
	v_cvt_pk_bf16_f32 v144, v180, v181
	v_cvt_pk_bf16_f32 v145, v182, v183
	v_sub_f32_e32 v184, v184, v120
	v_sub_f32_e32 v185, v185, v120
	v_sub_f32_e32 v186, v186, v120
	v_sub_f32_e32 v187, v187, v120
	v_sub_f32_e32 v188, v188, v120
	v_sub_f32_e32 v189, v189, v120
	v_sub_f32_e32 v190, v190, v120
	v_sub_f32_e32 v191, v191, v120
	s_waitcnt lgkmcnt(4)
	v_mfma_f32_32x32x16_bf16 v[18:33], v[208:211], v[142:145], v[18:33]
	v_mfma_f32_32x32x16_bf16 v[2:17], v[232:235], v[142:145], v[2:17]
	ds_read_b128 v[208:211], v231 offset:36192
	ds_read_b128 v[232:235], v231 offset:40800
	v_exp_f32_e32 v184, v184
	v_exp_f32_e32 v185, v185
	v_exp_f32_e32 v186, v186
	v_exp_f32_e32 v187, v187
	v_exp_f32_e32 v188, v188
	v_exp_f32_e32 v189, v189
	v_exp_f32_e32 v190, v190
	v_exp_f32_e32 v191, v191
	v_add_f32_e32 v141, v176, v177
	v_add_f32_e32 v154, v178, v179
	v_add_f32_e32 v212, v180, v181
	v_add_f32_e32 v213, v182, v183
	v_add_f32_e32 v141, v141, v154
	v_add_f32_e32 v212, v212, v213
	v_add_f32_e32 v230, v141, v212
	v_cvt_pk_bf16_f32 v146, v184, v185
	v_cvt_pk_bf16_f32 v147, v186, v187
	v_cvt_pk_bf16_f32 v148, v188, v189
	v_cvt_pk_bf16_f32 v149, v190, v191
	v_sub_f32_e32 v192, v192, v120
	v_sub_f32_e32 v193, v193, v120
	v_sub_f32_e32 v194, v194, v120
	v_sub_f32_e32 v195, v195, v120
	v_sub_f32_e32 v196, v196, v120
	v_sub_f32_e32 v197, v197, v120
	v_sub_f32_e32 v198, v198, v120
	v_sub_f32_e32 v199, v199, v120
	s_waitcnt lgkmcnt(4)
; DI unsigned pk2(float a, float b) { f32x2 v = {a, b}; return __builtin_bit_cast(unsigned, __builtin_convertvector(v, bf2_t)); }
; #define MFMA32(a, b, c) __builtin_amdgcn_mfma_f32_32x32x16_bf16((a), (b), (c), 0, 0, 0)
; DI float fexp2(float x) { return __builtin_amdgcn_exp2f(x); }
;     ...
;                 if (MODE == 0 && (64 * kt + 63 > q0 + 32 * w)) {
; #pragma unroll
;                     for (int mt = 0; mt < 2; ++mt)
; #pragma unroll
;                         for (int qd = 0; qd < 4; ++qd)
; #pragma unroll
;                             for (int e = 0; e < 4; ++e)
;                                 if (64 * kt + 32 * mt + 8 * qd + 4 * h + e > qidx) s4[mt][qd][e] = -INFINITY;
;                 }
;     ...
;                 for (int s2 = 0; s2 < 4; ++s2) {
;                     const int mt = s2 >> 1, s = s2 & 1;
;                     f32x4 da = s4[mt][2 * s] + nm4, db = s4[mt][2 * s + 1] + nm4;
;                     da.x = fexp2(da.x); da.y = fexp2(da.y); da.z = fexp2(da.z); da.w = fexp2(da.w);
;                     db.x = fexp2(db.x); db.y = fexp2(db.y); db.z = fexp2(db.z); db.w = fexp2(db.w);
;                     ps4 += da; ps4 += db;
;                     u32x4 pp;
;                     pp.x = pk2(da.x, da.y); pp.y = pk2(da.z, da.w); pp.z = pk2(db.x, db.y); pp.w = pk2(db.z, db.w);
;                     const bf16x8 pfr = __builtin_bit_cast(bf16x8, pp);
;                     const s16x4 a0 = *(const s16x4*)(sV + r * LS + 16 * s2 + 4 * h), a1 = *(const s16x4*)(sV + r * LS + 16 * s2 + 8 + 4 * h);
;                     const s16x4 b0 = *(const s16x4*)(sV + (32 + r) * LS + 16 * s2 + 4 * h), b1 = *(const s16x4*)(sV + (32 + r) * LS + 16 * s2 + 8 + 4 * h);
;                     const bf16x8 v0 = __builtin_shufflevector(a0, a1, 0, 1, 2, 3, 4, 5, 6, 7), v1 = __builtin_shufflevector(b0, b1, 0, 1, 2, 3, 4, 5, 6, 7);
;                     o0 = MFMA32(v0, pfr, o0);
;                     o1 = MFMA32(v1, pfr, o1);
;                 }
;                 lsum = lsum * alpha + ((ps4.x + ps4.y) + (ps4.z + ps4.w));
	v_mfma_f32_32x32x16_bf16 v[18:33], v[236:239], v[146:149], v[18:33]
	v_mfma_f32_32x32x16_bf16 v[2:17], v[240:243], v[146:149], v[2:17]
	v_exp_f32_e32 v192, v192
	v_exp_f32_e32 v193, v193
	v_exp_f32_e32 v194, v194
	v_exp_f32_e32 v195, v195
	v_exp_f32_e32 v196, v196
	v_exp_f32_e32 v197, v197
	v_exp_f32_e32 v198, v198
	v_exp_f32_e32 v199, v199
	v_add_f32_e32 v141, v184, v185
	v_add_f32_e32 v154, v186, v187
	v_add_f32_e32 v212, v188, v189
	v_add_f32_e32 v213, v190, v191
	v_add_f32_e32 v141, v141, v154
	v_add_f32_e32 v212, v212, v213
	v_add_f32_e32 v141, v141, v212
	v_add_f32_e32 v230, v230, v141
	v_cvt_pk_bf16_f32 v150, v192, v193
	v_cvt_pk_bf16_f32 v151, v194, v195
	v_cvt_pk_bf16_f32 v152, v196, v197
	v_cvt_pk_bf16_f32 v153, v198, v199
	v_sub_f32_e32 v200, v200, v120
	v_sub_f32_e32 v201, v201, v120
	v_sub_f32_e32 v202, v202, v120
	v_sub_f32_e32 v203, v203, v120
	v_sub_f32_e32 v204, v204, v120
	v_sub_f32_e32 v205, v205, v120
	v_sub_f32_e32 v206, v206, v120
	v_sub_f32_e32 v207, v207, v120
	s_waitcnt lgkmcnt(2)
	v_mfma_f32_32x32x16_bf16 v[18:33], v[244:247], v[150:153], v[18:33]
	v_mfma_f32_32x32x16_bf16 v[2:17], v[248:251], v[150:153], v[2:17]
	v_exp_f32_e32 v200, v200
	v_exp_f32_e32 v201, v201
	v_exp_f32_e32 v202, v202
	v_exp_f32_e32 v203, v203
	v_exp_f32_e32 v204, v204
	v_exp_f32_e32 v205, v205
	v_exp_f32_e32 v206, v206
	v_exp_f32_e32 v207, v207
	v_add_f32_e32 v141, v192, v193
	v_add_f32_e32 v154, v194, v195
	v_add_f32_e32 v212, v196, v197
	v_add_f32_e32 v213, v198, v199
	v_add_f32_e32 v141, v141, v154
	v_add_f32_e32 v212, v212, v213
	v_add_f32_e32 v141, v141, v212
	v_add_f32_e32 v230, v230, v141
	v_cvt_pk_bf16_f32 v142, v200, v201
	v_cvt_pk_bf16_f32 v143, v202, v203
	v_cvt_pk_bf16_f32 v144, v204, v205
	v_cvt_pk_bf16_f32 v145, v206, v207
	v_add_f32_e32 v141, v200, v201
	v_add_f32_e32 v154, v202, v203
	v_add_f32_e32 v212, v204, v205
	v_add_f32_e32 v213, v206, v207
	s_waitcnt lgkmcnt(0)
	v_mfma_f32_32x32x16_bf16 v[18:33], v[208:211], v[142:145], v[18:33]
	v_mfma_f32_32x32x16_bf16 v[2:17], v[232:235], v[142:145], v[2:17]
	v_add_f32_e32 v141, v141, v154
	v_add_f32_e32 v212, v212, v213
	v_add_f32_e32 v141, v141, v212
	v_add_f32_e32 v230, v230, v141
	v_fma_f32 v135, v135, v122, v230
	v_mov_b32_e32 v122, v120
	s_waitcnt vmcnt(0)
	ds_write2_b64 v130, v[78:79], v[80:81] offset1:2
	ds_write2_b64 v132, v[82:83], v[84:85] offset1:2
	ds_write_b128 v127, v[66:69] offset:22784
	ds_write_b128 v128, v[70:73] offset:22784
	ds_write_b128 v129, v[74:77] offset:22784
	s_add_i32 s12, s12, 1
	s_add_i32 s16, s16, 64
	s_branch .Lm3_even
.Lm3_final:
	v_cmp_le_i32_e32 vcc, s16, v133
	s_waitcnt lgkmcnt(0)
	s_barrier
	s_and_saveexec_b64 s[12:13], vcc
	s_cbranch_execz .Lm3_done
	ds_read_b128 v[208:211], v231 offset:36096
	ds_read_b128 v[232:235], v231 offset:40704
	ds_read_b128 v[236:239], v231 offset:36128
	ds_read_b128 v[240:243], v231 offset:40736
	ds_read_b128 v[244:247], v231 offset:36160
	ds_read_b128 v[248:251], v231 offset:40768
	s_add_i32 s14, s16, 63
	v_cmp_gt_i32_e32 vcc, s14, v125
	s_and_saveexec_b64 s[14:15], vcc
	s_cbranch_execz .Lm3_nomask_f
	v_sub_u32_e32 v213, v126, v123
	v_subrev_u32_e32 v213, s16, v213
	v_cmp_le_i32_e32 vcc, 0, v213
	s_nop 1
	v_cndmask_b32_e32 v176, v228, v176, vcc
	v_cmp_le_i32_e32 vcc, 1, v213
	s_nop 1
	v_cndmask_b32_e32 v177, v228, v177, vcc
	v_cmp_le_i32_e32 vcc, 2, v213
	s_nop 1
	v_cndmask_b32_e32 v178, v228, v178, vcc
	v_cmp_le_i32_e32 vcc, 3, v213
	s_nop 1
	v_cndmask_b32_e32 v179, v228, v179, vcc
	v_cmp_le_i32_e32 vcc, 8, v213
	s_nop 1
	v_cndmask_b32_e32 v180, v228, v180, vcc
	v_cmp_le_i32_e32 vcc, 9, v213
	s_nop 1
	v_cndmask_b32_e32 v181, v228, v181, vcc
	v_cmp_le_i32_e32 vcc, 10, v213
	s_nop 1
	v_cndmask_b32_e32 v182, v228, v182, vcc
	v_cmp_le_i32_e32 vcc, 11, v213
	s_nop 1
	v_cndmask_b32_e32 v183, v228, v183, vcc
	v_cmp_le_i32_e32 vcc, 16, v213
	s_nop 1
	v_cndmask_b32_e32 v184, v228, v184, vcc
	v_cmp_le_i32_e32 vcc, 17, v213
	s_nop 1
	v_cndmask_b32_e32 v185, v228, v185, vcc
	v_cmp_le_i32_e32 vcc, 18, v213
	s_nop 1
	v_cndmask_b32_e32 v186, v228, v186, vcc
	v_cmp_le_i32_e32 vcc, 19, v213
	s_nop 1
	v_cndmask_b32_e32 v187, v228, v187, vcc
	v_cmp_le_i32_e32 vcc, 24, v213
	s_nop 1
	v_cndmask_b32_e32 v188, v228, v188, vcc
	v_cmp_le_i32_e32 vcc, 25, v213
	s_nop 1
	v_cndmask_b32_e32 v189, v228, v189, vcc
	v_cmp_le_i32_e32 vcc, 26, v213
	s_nop 1
	v_cndmask_b32_e32 v190, v228, v190, vcc
	v_cmp_le_i32_e32 vcc, 27, v213
	s_nop 1
	v_cndmask_b32_e32 v191, v228, v191, vcc
	v_cmp_le_i32_e32 vcc, 32, v213
	s_nop 1
	v_cndmask_b32_e32 v192, v228, v192, vcc
	v_cmp_le_i32_e32 vcc, 33, v213
	s_nop 1
	v_cndmask_b32_e32 v193, v228, v193, vcc
	v_cmp_le_i32_e32 vcc, 34, v213
	s_nop 1
	v_cndmask_b32_e32 v194, v228, v194, vcc
	v_cmp_le_i32_e32 vcc, 35, v213
	s_nop 1
	v_cndmask_b32_e32 v195, v228, v195, vcc
	v_cmp_le_i32_e32 vcc, 40, v213
	s_nop 1
	v_cndmask_b32_e32 v196, v228, v196, vcc
	v_cmp_le_i32_e32 vcc, 41, v213
	s_nop 1
	v_cndmask_b32_e32 v197, v228, v197, vcc
	v_cmp_le_i32_e32 vcc, 42, v213
	s_nop 1
	v_cndmask_b32_e32 v198, v228, v198, vcc
	v_cmp_le_i32_e32 vcc, 43, v213
	s_nop 1
	v_cndmask_b32_e32 v199, v228, v199, vcc
	v_cmp_le_i32_e32 vcc, 48, v213
	s_nop 1
	v_cndmask_b32_e32 v200, v228, v200, vcc
	v_cmp_le_i32_e32 vcc, 49, v213
	s_nop 1
	v_cndmask_b32_e32 v201, v228, v201, vcc
	v_cmp_le_i32_e32 vcc, 50, v213
	s_nop 1
	v_cndmask_b32_e32 v202, v228, v202, vcc
	v_cmp_le_i32_e32 vcc, 51, v213
	s_nop 1
	v_cndmask_b32_e32 v203, v228, v203, vcc
	v_cmp_le_i32_e32 vcc, 56, v213
	s_nop 1
	v_cndmask_b32_e32 v204, v228, v204, vcc
	v_cmp_le_i32_e32 vcc, 57, v213
	s_nop 1
	v_cndmask_b32_e32 v205, v228, v205, vcc
	v_cmp_le_i32_e32 vcc, 58, v213
	s_nop 1
	v_cndmask_b32_e32 v206, v228, v206, vcc
	v_cmp_le_i32_e32 vcc, 59, v213
	s_nop 1
	v_cndmask_b32_e32 v207, v228, v207, vcc
; DI unsigned pk2(float a, float b) { f32x2 v = {a, b}; return __builtin_bit_cast(unsigned, __builtin_convertvector(v, bf2_t)); }
; #define MFMA32(a, b, c) __builtin_amdgcn_mfma_f32_32x32x16_bf16((a), (b), (c), 0, 0, 0)
;     ...
;                 float mx = fmaxf(s4[0][0].x, s4[1][0].x);
; #pragma unroll
;                 for (int qd = 0; qd < 4; ++qd) {
;                     mx = fmaxf(fmaxf(mx, s4[0][qd].y), s4[1][qd].y);
;                     mx = fmaxf(fmaxf(mx, s4[0][qd].z), s4[1][qd].z);
;                     mx = fmaxf(fmaxf(mx, s4[0][qd].w), s4[1][qd].w);
;                     if (qd < 3) mx = fmaxf(fmaxf(mx, s4[0][qd + 1].x), s4[1][qd + 1].x);
;                 }
;                 mx = xhalf_max(mx);
;                 const float mn = fmaxf(m, mx), alpha = fexp2(m - mn);
;                 m = mn;
;                 f32x4 ps4 = {0.f, 0.f, 0.f, 0.f};
;                 const float nmn = -mn;
;                 const f32x4 nm4 = {nmn, nmn, nmn, nmn};
;                 if (__builtin_amdgcn_ballot_w64(alpha != 1.f) != 0) { o0 *= alpha; o1 *= alpha; }
; #pragma unroll
;                 for (int s2 = 0; s2 < 4; ++s2) {
;                     const int mt = s2 >> 1, s = s2 & 1;
;                     f32x4 da = s4[mt][2 * s] + nm4, db = s4[mt][2 * s + 1] + nm4;
;                     da.x = fexp2(da.x); da.y = fexp2(da.y); da.z = fexp2(da.z); da.w = fexp2(da.w);
;                     db.x = fexp2(db.x); db.y = fexp2(db.y); db.z = fexp2(db.z); db.w = fexp2(db.w);
;                     ps4 += da; ps4 += db;
;                     u32x4 pp;
;                     pp.x = pk2(da.x, da.y); pp.y = pk2(da.z, da.w); pp.z = pk2(db.x, db.y); pp.w = pk2(db.z, db.w);
;                     const bf16x8 pfr = __builtin_bit_cast(bf16x8, pp);
;                     const s16x4 a0 = *(const s16x4*)(sV + r * LS + 16 * s2 + 4 * h), a1 = *(const s16x4*)(sV + r * LS + 16 * s2 + 8 + 4 * h);
;                     const s16x4 b0 = *(const s16x4*)(sV + (32 + r) * LS + 16 * s2 + 4 * h), b1 = *(const s16x4*)(sV + (32 + r) * LS + 16 * s2 + 8 + 4 * h);
;                     const bf16x8 v0 = __builtin_shufflevector(a0, a1, 0, 1, 2, 3, 4, 5, 6, 7), v1 = __builtin_shufflevector(b0, b1, 0, 1, 2, 3, 4, 5, 6, 7);
;                     o0 = MFMA32(v0, pfr, o0);
;                     o1 = MFMA32(v1, pfr, o1);
;                 }
;                 lsum = lsum * alpha + ((ps4.x + ps4.y) + (ps4.z + ps4.w));
.Lm3_nomask_f:
	s_or_b64 exec, exec, s[14:15]
	v_max3_f32 v120, v176, v177, v178
	v_max3_f32 v141, v179, v180, v181
	v_max3_f32 v154, v182, v183, v184
	v_max3_f32 v212, v185, v186, v187
	v_max3_f32 v120, v120, v188, v189
	v_max3_f32 v141, v141, v190, v191
	v_max3_f32 v154, v154, v192, v193
	v_max3_f32 v212, v212, v194, v195
	v_max3_f32 v120, v120, v196, v197
	v_max3_f32 v141, v141, v198, v199
	v_max3_f32 v154, v154, v200, v201
	v_max3_f32 v212, v212, v202, v203
	v_max3_f32 v120, v120, v204, v205
	v_max3_f32 v141, v141, v206, v207
	v_max3_f32 v120, v120, v141, v154
	v_max_f32_e32 v120, v120, v212
	v_mov_b32_e32 v141, v120
	s_nop 1
	v_permlane32_swap_b32_e32 v120, v141
	v_max3_f32 v120, v122, v120, v141
	v_sub_f32_e32 v122, v122, v120
	v_exp_f32_e32 v122, v122
	s_nop 0
	v_cmp_neq_f32_e32 vcc, 1.0, v122
	s_cbranch_vccz .Lm3_noresc_f
	v_pk_mul_f32 v[32:33], v[32:33], v[122:123] op_sel_hi:[1,0]
	v_pk_mul_f32 v[30:31], v[30:31], v[122:123] op_sel_hi:[1,0]
	v_pk_mul_f32 v[28:29], v[28:29], v[122:123] op_sel_hi:[1,0]
	v_pk_mul_f32 v[26:27], v[26:27], v[122:123] op_sel_hi:[1,0]
	v_pk_mul_f32 v[24:25], v[24:25], v[122:123] op_sel_hi:[1,0]
	v_pk_mul_f32 v[22:23], v[22:23], v[122:123] op_sel_hi:[1,0]
	v_pk_mul_f32 v[20:21], v[20:21], v[122:123] op_sel_hi:[1,0]
	v_pk_mul_f32 v[18:19], v[18:19], v[122:123] op_sel_hi:[1,0]
	v_pk_mul_f32 v[16:17], v[16:17], v[122:123] op_sel_hi:[1,0]
	v_pk_mul_f32 v[14:15], v[14:15], v[122:123] op_sel_hi:[1,0]
	v_pk_mul_f32 v[12:13], v[12:13], v[122:123] op_sel_hi:[1,0]
	v_pk_mul_f32 v[10:11], v[10:11], v[122:123] op_sel_hi:[1,0]
	v_pk_mul_f32 v[8:9], v[8:9], v[122:123] op_sel_hi:[1,0]
	v_pk_mul_f32 v[6:7], v[6:7], v[122:123] op_sel_hi:[1,0]
	v_pk_mul_f32 v[4:5], v[4:5], v[122:123] op_sel_hi:[1,0]
	v_pk_mul_f32 v[2:3], v[2:3], v[122:123] op_sel_hi:[1,0]
.Lm3_noresc_f:
	v_sub_f32_e32 v176, v176, v120
	v_sub_f32_e32 v177, v177, v120
	v_sub_f32_e32 v178, v178, v120
	v_sub_f32_e32 v179, v179, v120
	v_sub_f32_e32 v180, v180, v120
	v_sub_f32_e32 v181, v181, v120
	v_sub_f32_e32 v182, v182, v120
	v_sub_f32_e32 v183, v183, v120
	v_exp_f32_e32 v176, v176
	v_exp_f32_e32 v177, v177
	v_exp_f32_e32 v178, v178
	v_exp_f32_e32 v179, v179
	v_exp_f32_e32 v180, v180
	v_exp_f32_e32 v181, v181
	v_exp_f32_e32 v182, v182
	v_exp_f32_e32 v183, v183
	v_cvt_pk_bf16_f32 v142, v176, v177
	v_cvt_pk_bf16_f32 v143, v178, v179
	v_cvt_pk_bf16_f32 v144, v180, v181
	v_cvt_pk_bf16_f32 v145, v182, v183
	v_sub_f32_e32 v184, v184, v120
	v_sub_f32_e32 v185, v185, v120
	v_sub_f32_e32 v186, v186, v120
	v_sub_f32_e32 v187, v187, v120
	v_sub_f32_e32 v188, v188, v120
	v_sub_f32_e32 v189, v189, v120
	v_sub_f32_e32 v190, v190, v120
	v_sub_f32_e32 v191, v191, v120
	s_waitcnt lgkmcnt(4)
	v_mfma_f32_32x32x16_bf16 v[18:33], v[208:211], v[142:145], v[18:33]
	v_mfma_f32_32x32x16_bf16 v[2:17], v[232:235], v[142:145], v[2:17]
	ds_read_b128 v[208:211], v231 offset:36192
	ds_read_b128 v[232:235], v231 offset:40800
	v_exp_f32_e32 v184, v184
	v_exp_f32_e32 v185, v185
	v_exp_f32_e32 v186, v186
	v_exp_f32_e32 v187, v187
	v_exp_f32_e32 v188, v188
	v_exp_f32_e32 v189, v189
	v_exp_f32_e32 v190, v190
	v_exp_f32_e32 v191, v191
	v_add_f32_e32 v141, v176, v177
	v_add_f32_e32 v154, v178, v179
	v_add_f32_e32 v212, v180, v181
	v_add_f32_e32 v213, v182, v183
	v_add_f32_e32 v141, v141, v154
	v_add_f32_e32 v212, v212, v213
	v_add_f32_e32 v230, v141, v212
	v_cvt_pk_bf16_f32 v146, v184, v185
	v_cvt_pk_bf16_f32 v147, v186, v187
	v_cvt_pk_bf16_f32 v148, v188, v189
	v_cvt_pk_bf16_f32 v149, v190, v191
	v_sub_f32_e32 v192, v192, v120
	v_sub_f32_e32 v193, v193, v120
	v_sub_f32_e32 v194, v194, v120
	v_sub_f32_e32 v195, v195, v120
	v_sub_f32_e32 v196, v196, v120
	v_sub_f32_e32 v197, v197, v120
	v_sub_f32_e32 v198, v198, v120
	v_sub_f32_e32 v199, v199, v120
	s_waitcnt lgkmcnt(4)
	v_mfma_f32_32x32x16_bf16 v[18:33], v[236:239], v[146:149], v[18:33]
	v_mfma_f32_32x32x16_bf16 v[2:17], v[240:243], v[146:149], v[2:17]
	v_exp_f32_e32 v192, v192
	v_exp_f32_e32 v193, v193
	v_exp_f32_e32 v194, v194
	v_exp_f32_e32 v195, v195
	v_exp_f32_e32 v196, v196
	v_exp_f32_e32 v197, v197
	v_exp_f32_e32 v198, v198
	v_exp_f32_e32 v199, v199
	v_add_f32_e32 v141, v184, v185
	v_add_f32_e32 v154, v186, v187
	v_add_f32_e32 v212, v188, v189
	v_add_f32_e32 v213, v190, v191
	v_add_f32_e32 v141, v141, v154
	v_add_f32_e32 v212, v212, v213
	v_add_f32_e32 v141, v141, v212
	v_add_f32_e32 v230, v230, v141
	v_cvt_pk_bf16_f32 v150, v192, v193
	v_cvt_pk_bf16_f32 v151, v194, v195
	v_cvt_pk_bf16_f32 v152, v196, v197
	v_cvt_pk_bf16_f32 v153, v198, v199
	v_sub_f32_e32 v200, v200, v120
	v_sub_f32_e32 v201, v201, v120
	v_sub_f32_e32 v202, v202, v120
	v_sub_f32_e32 v203, v203, v120
	v_sub_f32_e32 v204, v204, v120
	v_sub_f32_e32 v205, v205, v120
	v_sub_f32_e32 v206, v206, v120
	v_sub_f32_e32 v207, v207, v120
	s_waitcnt lgkmcnt(2)
	v_mfma_f32_32x32x16_bf16 v[18:33], v[244:247], v[150:153], v[18:33]
	v_mfma_f32_32x32x16_bf16 v[2:17], v[248:251], v[150:153], v[2:17]
	v_exp_f32_e32 v200, v200
	v_exp_f32_e32 v201, v201
	v_exp_f32_e32 v202, v202
	v_exp_f32_e32 v203, v203
	v_exp_f32_e32 v204, v204
	v_exp_f32_e32 v205, v205
	v_exp_f32_e32 v206, v206
	v_exp_f32_e32 v207, v207
	v_add_f32_e32 v141, v192, v193
	v_add_f32_e32 v154, v194, v195
	v_add_f32_e32 v212, v196, v197
	v_add_f32_e32 v213, v198, v199
	v_add_f32_e32 v141, v141, v154
	v_add_f32_e32 v212, v212, v213
	v_add_f32_e32 v141, v141, v212
	v_add_f32_e32 v230, v230, v141
	v_cvt_pk_bf16_f32 v142, v200, v201
	v_cvt_pk_bf16_f32 v143, v202, v203
	v_cvt_pk_bf16_f32 v144, v204, v205
	v_cvt_pk_bf16_f32 v145, v206, v207
	v_add_f32_e32 v141, v200, v201
	v_add_f32_e32 v154, v202, v203
	v_add_f32_e32 v212, v204, v205
	v_add_f32_e32 v213, v206, v207
	s_waitcnt lgkmcnt(0)
	v_mfma_f32_32x32x16_bf16 v[18:33], v[208:211], v[142:145], v[18:33]
	v_mfma_f32_32x32x16_bf16 v[2:17], v[232:235], v[142:145], v[2:17]
	v_add_f32_e32 v141, v141, v154
	v_add_f32_e32 v212, v212, v213
	v_add_f32_e32 v141, v141, v212
	v_add_f32_e32 v230, v230, v141
	v_fma_f32 v135, v135, v122, v230
	v_mov_b32_e32 v122, v120
; DI unsigned pk2(float a, float b) { f32x2 v = {a, b}; return __builtin_bit_cast(unsigned, __builtin_convertvector(v, bf2_t)); }
; DI float bflo(unsigned u) { return __uint_as_float(u << 16); }
; DI float bfhi(unsigned u) { return __uint_as_float(u & 0xffff0000u); }
; DI float xhalf_other(float x, int h) { auto r = __builtin_amdgcn_permlane32_swap(__float_as_uint(x), __float_as_uint(x), false, false); return h ? __uint_as_float(r[0]) : __uint_as_float(r[1]); }
;     ...
;     if (MODE != 1) {
;         const float lt = lsum + xhalf_other(lsum, h), inv = __builtin_amdgcn_rcpf(lt);
;         o0 *= inv; o1 *= inv;
;     }
;     bf16_t* yrow = yb + (size_t)(32 * w + r) * 1024 + 4 * h;
;     const bf16_t* grow = gt + (size_t)(32 * w + r) * 1024 + 4 * h;
;     u32x2 gv[2][4];
; #pragma unroll
;     for (int nt = 0; nt < 2; ++nt)
; #pragma unroll
;         for (int qd = 0; qd < 4; ++qd) gv[nt][qd] = *(const u32x2*)(grow + 32 * nt + 8 * qd);
; #pragma unroll
;     for (int nt = 0; nt < 2; ++nt)
; #pragma unroll
;         for (int qd = 0; qd < 4; ++qd) {
;             const u32x2 g = gv[nt][qd];
;             const f32x16& o = nt ? o1 : o0;
;             u32x2 v;
;             v.x = pk2(o[4 * qd] * bflo(g.x), o[4 * qd + 1] * bfhi(g.x));
;             v.y = pk2(o[4 * qd + 2] * bflo(g.y), o[4 * qd + 3] * bfhi(g.y));
;             *(u32x2*)(yrow + 32 * nt + 8 * qd) = v;
;         }
.Lm3_done:
	s_or_b64 exec, exec, s[12:13]
.LBB0_785:
	s_mov_b32 s57, s49
	s_lshl_b64 s[4:5], s[94:95], 11
	s_lshl_b64 s[6:7], s[56:57], 24
	s_or_b64 s[4:5], s[4:5], s[6:7]
	s_add_u32 s6, s61, s4
	s_addc_u32 s7, s70, s5
	s_add_u32 s4, s69, s4
	v_mov_b32_e32 v0, v135
	v_mov_b32_e32 v34, v135
	s_addc_u32 s5, s60, s5
	s_lshl_b32 s8, s79, 7
	v_permlane32_swap_b32_e32 v0, v34
	v_cmp_eq_u32_e32 vcc, 0, v121
	s_add_u32 s4, s4, s8
	s_addc_u32 s5, s5, 0
	v_cndmask_b32_e32 v0, v0, v34, vcc
	v_add_f32_e32 v0, v135, v0
	v_lshlrev_b64 v[42:43], 11, v[110:111]
	v_rcp_f32_e32 v44, v0
	v_lshl_add_u64 v[34:35], s[4:5], 0, v[42:43]
	v_lshlrev_b32_e32 v0, 1, v123
	v_lshl_add_u64 v[34:35], v[34:35], 0, v[0:1]
	flat_load_dwordx2 v[46:47], v[34:35]
	flat_load_dwordx2 v[48:49], v[34:35] offset:16
	flat_load_dwordx2 v[50:51], v[34:35] offset:32
	flat_load_dwordx2 v[52:53], v[34:35] offset:48
	flat_load_dwordx2 v[40:41], v[34:35] offset:64
	flat_load_dwordx2 v[38:39], v[34:35] offset:80
	flat_load_dwordx2 v[36:37], v[34:35] offset:96
	s_nop 0
	flat_load_dwordx2 v[34:35], v[34:35] offset:112
	s_add_u32 s6, s6, s8
	s_addc_u32 s7, s7, 0
	v_pk_mul_f32 v[20:21], v[20:21], v[44:45] op_sel_hi:[1,0]
	v_pk_mul_f32 v[18:19], v[18:19], v[44:45] op_sel_hi:[1,0]
	v_lshl_add_u64 v[42:43], s[6:7], 0, v[42:43]
	v_lshl_add_u64 v[42:43], v[42:43], 0, v[0:1]
	v_pk_mul_f32 v[24:25], v[24:25], v[44:45] op_sel_hi:[1,0]
	v_pk_mul_f32 v[22:23], v[22:23], v[44:45] op_sel_hi:[1,0]
	v_pk_mul_f32 v[28:29], v[28:29], v[44:45] op_sel_hi:[1,0]
	v_pk_mul_f32 v[26:27], v[26:27], v[44:45] op_sel_hi:[1,0]
	v_pk_mul_f32 v[32:33], v[32:33], v[44:45] op_sel_hi:[1,0]
	v_pk_mul_f32 v[30:31], v[30:31], v[44:45] op_sel_hi:[1,0]
	v_pk_mul_f32 v[16:17], v[16:17], v[44:45] op_sel_hi:[1,0]
	v_pk_mul_f32 v[14:15], v[14:15], v[44:45] op_sel_hi:[1,0]
	v_pk_mul_f32 v[12:13], v[12:13], v[44:45] op_sel_hi:[1,0]
	v_pk_mul_f32 v[10:11], v[10:11], v[44:45] op_sel_hi:[1,0]
	v_pk_mul_f32 v[8:9], v[8:9], v[44:45] op_sel_hi:[1,0]
	v_pk_mul_f32 v[6:7], v[6:7], v[44:45] op_sel_hi:[1,0]
	v_pk_mul_f32 v[4:5], v[4:5], v[44:45] op_sel_hi:[1,0]
	v_pk_mul_f32 v[2:3], v[2:3], v[44:45] op_sel_hi:[1,0]
	s_mov_b32 s95, 0x7fffffe0
	s_waitcnt vmcnt(0) lgkmcnt(0)
	v_lshlrev_b32_e32 v54, 16, v46
	v_and_b32_e32 v55, 0xffff0000, v46
	v_lshlrev_b32_e32 v46, 16, v47
	v_and_b32_e32 v47, 0xffff0000, v47
	v_pk_mul_f32 v[18:19], v[18:19], v[54:55]
	v_pk_mul_f32 v[20:21], v[20:21], v[46:47]
	v_cvt_pk_bf16_f32 v18, v18, v19
	v_cvt_pk_bf16_f32 v19, v20, v21
	flat_store_dwordx2 v[42:43], v[18:19]
	v_lshlrev_b32_e32 v18, 16, v48
	v_and_b32_e32 v19, 0xffff0000, v48
	v_lshlrev_b32_e32 v20, 16, v49
	v_and_b32_e32 v21, 0xffff0000, v49
	v_pk_mul_f32 v[18:19], v[22:23], v[18:19]
	v_pk_mul_f32 v[20:21], v[24:25], v[20:21]
	v_cvt_pk_bf16_f32 v18, v18, v19
	v_cvt_pk_bf16_f32 v19, v20, v21
	flat_store_dwordx2 v[42:43], v[18:19] offset:16
	v_lshlrev_b32_e32 v18, 16, v50
	v_and_b32_e32 v19, 0xffff0000, v50
	v_lshlrev_b32_e32 v20, 16, v51
	v_and_b32_e32 v21, 0xffff0000, v51
	v_pk_mul_f32 v[18:19], v[26:27], v[18:19]
	v_pk_mul_f32 v[20:21], v[28:29], v[20:21]
	v_cvt_pk_bf16_f32 v18, v18, v19
	v_cvt_pk_bf16_f32 v19, v20, v21
	flat_store_dwordx2 v[42:43], v[18:19] offset:32
	v_lshlrev_b32_e32 v18, 16, v52
	v_and_b32_e32 v19, 0xffff0000, v52
	v_lshlrev_b32_e32 v20, 16, v53
	v_and_b32_e32 v21, 0xffff0000, v53
	v_pk_mul_f32 v[18:19], v[30:31], v[18:19]
	v_pk_mul_f32 v[20:21], v[32:33], v[20:21]
	v_cvt_pk_bf16_f32 v18, v18, v19
	v_cvt_pk_bf16_f32 v19, v20, v21
	flat_store_dwordx2 v[42:43], v[18:19] offset:48
